# adds: band softmax far-tile path trimmed (max3 tree, bias const and ones kept in registers); GEMM K-loops: one static priority raise for waves 4-7 instead of per-segment setprio toggles
# baseline (speedup 1.0000x reference)
.LBB0_54:
	s_cmp_eq_u32 s54, 1
	s_cbranch_scc0 .Lg4_noprio
	s_setprio 1

.LBB0_62:
	s_add_u32 s36, s42, s50
	s_addc_u32 s37, s43, s51
	s_add_u32 s36, s36, 0x100
	s_addc_u32 s37, s37, 0
	s_add_u32 s65, s23, s50
	s_addc_u32 s66, s24, s51
	s_add_i32 s67, 0, 0x10000
	s_cmpk_eq_i32 s50, 0xf00
	s_cselect_b32 s53, s47, s37
	s_cselect_b32 s52, s60, s36
	s_cselect_b32 s37, s45, s66
	s_cselect_b32 s36, s61, s65
	s_add_i32 s65, 0, 0x14000
	v_add_u32_e32 v154, s67, v140
	v_add_u32_e32 v242, s67, v240
	v_add_u32_e32 v158, s65, v140
	v_add_u32_e32 v243, s65, v240
	ds_read_b128 v[142:145], v154
	ds_read_b128 v[146:149], v242
	ds_read_b128 v[150:153], v154 offset:2048
	ds_read_b128 v[154:157], v242 offset:2048
	ds_read_b128 v[162:165], v158
	ds_read_b128 v[170:173], v243
	ds_read_b128 v[174:177], v158 offset:2048
	ds_read_b128 v[178:181], v243 offset:2048
	v_lshl_add_u64 v[158:159], v[138:139], 0, s[50:51]
	s_add_i32 m0, s82, 0xc000
	ds_read_b128 v[182:185], v141
	ds_read_b128 v[190:193], v241
	ds_read_b128 v[194:197], v141 offset:2048
	ds_read_b128 v[198:201], v241 offset:2048
	ds_read_b128 v[216:219], v141 offset:4096
	ds_read_b128 v[220:223], v241 offset:4096
	ds_read_b128 v[224:227], v141 offset:6144
	ds_read_b128 v[228:231], v241 offset:6144
	global_load_lds_dwordx4 v[158:159], off
	v_lshl_add_u64 v[158:159], v[136:137], 0, s[50:51]
	s_add_i32 m0, s82, 0xe000
	s_nop 0
	global_load_lds_dwordx4 v[158:159], off
	s_waitcnt vmcnt(8)
	s_waitcnt lgkmcnt(0)
	s_barrier
	s_nop 0
	s_waitcnt lgkmcnt(0)
	v_mfma_f32_16x16x32_bf16 v[90:93], v[142:145], v[182:185], v[90:93]
	v_mfma_f32_16x16x32_bf16 v[74:77], v[150:153], v[182:185], v[74:77]
	v_mfma_f32_16x16x32_bf16 v[94:97], v[142:145], v[194:197], v[94:97]
	v_mfma_f32_16x16x32_bf16 v[78:81], v[150:153], v[194:197], v[78:81]
	v_mfma_f32_16x16x32_bf16 v[102:105], v[142:145], v[216:219], v[102:105]
	v_mfma_f32_16x16x32_bf16 v[98:101], v[150:153], v[216:219], v[98:101]
	v_mfma_f32_16x16x32_bf16 v[118:121], v[142:145], v[224:227], v[118:121]
	v_mfma_f32_16x16x32_bf16 v[106:109], v[150:153], v[224:227], v[106:109]
	v_mfma_f32_16x16x32_bf16 v[90:93], v[146:149], v[190:193], v[90:93]
	v_mfma_f32_16x16x32_bf16 v[74:77], v[154:157], v[190:193], v[74:77]
	v_mfma_f32_16x16x32_bf16 v[94:97], v[146:149], v[198:201], v[94:97]
	v_mfma_f32_16x16x32_bf16 v[78:81], v[154:157], v[198:201], v[78:81]
	v_mfma_f32_16x16x32_bf16 v[102:105], v[146:149], v[220:223], v[102:105]
	v_mfma_f32_16x16x32_bf16 v[98:101], v[154:157], v[220:223], v[98:101]
	v_mfma_f32_16x16x32_bf16 v[118:121], v[146:149], v[228:231], v[118:121]
	v_mfma_f32_16x16x32_bf16 v[106:109], v[154:157], v[228:231], v[106:109]
	s_nop 0
	s_nop 0
	v_mfma_f32_16x16x32_bf16 v[6:9], v[162:165], v[182:185], v[6:9]
	v_mfma_f32_16x16x32_bf16 v[2:5], v[174:177], v[182:185], v[2:5]
	v_mfma_f32_16x16x32_bf16 v[14:17], v[162:165], v[194:197], v[14:17]
	v_mfma_f32_16x16x32_bf16 v[10:13], v[174:177], v[194:197], v[10:13]
	v_mfma_f32_16x16x32_bf16 v[22:25], v[162:165], v[216:219], v[22:25]
	v_mfma_f32_16x16x32_bf16 v[18:21], v[174:177], v[216:219], v[18:21]
	v_mfma_f32_16x16x32_bf16 v[30:33], v[162:165], v[224:227], v[30:33]
	v_mfma_f32_16x16x32_bf16 v[26:29], v[174:177], v[224:227], v[26:29]
	v_mfma_f32_16x16x32_bf16 v[6:9], v[170:173], v[190:193], v[6:9]
	v_mfma_f32_16x16x32_bf16 v[2:5], v[178:181], v[190:193], v[2:5]
	v_mfma_f32_16x16x32_bf16 v[14:17], v[170:173], v[198:201], v[14:17]
	v_mfma_f32_16x16x32_bf16 v[10:13], v[178:181], v[198:201], v[10:13]
	v_mfma_f32_16x16x32_bf16 v[22:25], v[170:173], v[220:223], v[22:25]
	v_mfma_f32_16x16x32_bf16 v[18:21], v[178:181], v[220:223], v[18:21]
	v_mfma_f32_16x16x32_bf16 v[30:33], v[170:173], v[228:231], v[30:33]
	v_mfma_f32_16x16x32_bf16 v[26:29], v[178:181], v[228:231], v[26:29]
	s_nop 0
	s_barrier
	s_add_i32 s66, s67, s80
	v_lshl_add_u64 v[158:159], s[36:37], 0, v[0:1]
	s_mov_b32 m0, s66
	ds_read_b128 v[182:185], v141 offset:16384
	ds_read_b128 v[190:193], v241 offset:16384
	ds_read_b128 v[194:197], v141 offset:18432
	ds_read_b128 v[198:201], v241 offset:18432
	ds_read_b128 v[216:219], v141 offset:20480
	ds_read_b128 v[220:223], v241 offset:20480
	ds_read_b128 v[224:227], v141 offset:22528
	ds_read_b128 v[228:231], v241 offset:22528
	global_load_lds_dwordx4 v[158:159], off
	s_add_i32 m0, s66, 0x2000
	s_add_u32 s66, s36, 0x80000
	v_lshl_add_u64 v[166:167], s[36:37], 0, v[130:131]
	s_addc_u32 s67, s37, 0
	s_add_i32 s65, s65, s80
	global_load_lds_dwordx4 v[166:167], off
	v_lshl_add_u64 v[202:203], s[66:67], 0, v[0:1]
	s_mov_b32 m0, s65
	v_lshl_add_u64 v[232:233], s[52:53], 0, v[130:131]
	global_load_lds_dwordx4 v[202:203], off
	v_lshl_add_u64 v[202:203], s[66:67], 0, v[130:131]
	s_add_i32 m0, s65, 0x2000
	s_nop 0
	global_load_lds_dwordx4 v[202:203], off
	v_lshl_add_u64 v[202:203], s[52:53], 0, v[0:1]
	s_mov_b32 m0, s82
	s_nop 0
	global_load_lds_dwordx4 v[202:203], off
	s_mov_b32 m0, s83
	s_nop 0
	global_load_lds_dwordx4 v[232:233], off
	s_waitcnt vmcnt(8)
	s_waitcnt lgkmcnt(0)
	s_barrier
	s_nop 0
	s_waitcnt lgkmcnt(0)
	v_mfma_f32_16x16x32_bf16 v[126:129], v[142:145], v[182:185], v[126:129]
	v_mfma_f32_16x16x32_bf16 v[122:125], v[150:153], v[182:185], v[122:125]
	v_mfma_f32_16x16x32_bf16 v[114:117], v[142:145], v[194:197], v[114:117]
	v_mfma_f32_16x16x32_bf16 v[110:113], v[150:153], v[194:197], v[110:113]
	v_mfma_f32_16x16x32_bf16 v[86:89], v[142:145], v[216:219], v[86:89]
	v_mfma_f32_16x16x32_bf16 v[82:85], v[150:153], v[216:219], v[82:85]
	v_mfma_f32_16x16x32_bf16 v[70:73], v[142:145], v[224:227], v[70:73]
	v_mfma_f32_16x16x32_bf16 v[66:69], v[150:153], v[224:227], v[66:69]
	v_mfma_f32_16x16x32_bf16 v[126:129], v[146:149], v[190:193], v[126:129]
	v_mfma_f32_16x16x32_bf16 v[122:125], v[154:157], v[190:193], v[122:125]
	v_mfma_f32_16x16x32_bf16 v[114:117], v[146:149], v[198:201], v[114:117]
	v_mfma_f32_16x16x32_bf16 v[110:113], v[154:157], v[198:201], v[110:113]
	v_mfma_f32_16x16x32_bf16 v[86:89], v[146:149], v[220:223], v[86:89]
	v_mfma_f32_16x16x32_bf16 v[82:85], v[154:157], v[220:223], v[82:85]
	v_mfma_f32_16x16x32_bf16 v[70:73], v[146:149], v[228:231], v[70:73]
	v_mfma_f32_16x16x32_bf16 v[66:69], v[154:157], v[228:231], v[66:69]
	s_nop 0
	s_nop 0
	v_mfma_f32_16x16x32_bf16 v[38:41], v[162:165], v[182:185], v[38:41]
	v_mfma_f32_16x16x32_bf16 v[34:37], v[174:177], v[182:185], v[34:37]
	v_mfma_f32_16x16x32_bf16 v[46:49], v[162:165], v[194:197], v[46:49]
	v_mfma_f32_16x16x32_bf16 v[42:45], v[174:177], v[194:197], v[42:45]
	v_mfma_f32_16x16x32_bf16 v[62:65], v[162:165], v[216:219], v[62:65]
	v_mfma_f32_16x16x32_bf16 v[54:57], v[174:177], v[216:219], v[54:57]
	v_mfma_f32_16x16x32_bf16 v[58:61], v[162:165], v[224:227], v[58:61]
	v_mfma_f32_16x16x32_bf16 v[50:53], v[174:177], v[224:227], v[50:53]
	v_mfma_f32_16x16x32_bf16 v[38:41], v[170:173], v[190:193], v[38:41]
	v_mfma_f32_16x16x32_bf16 v[34:37], v[178:181], v[190:193], v[34:37]
	v_mfma_f32_16x16x32_bf16 v[46:49], v[170:173], v[198:201], v[46:49]
	v_mfma_f32_16x16x32_bf16 v[42:45], v[178:181], v[198:201], v[42:45]
	v_mfma_f32_16x16x32_bf16 v[62:65], v[170:173], v[220:223], v[62:65]
	v_mfma_f32_16x16x32_bf16 v[54:57], v[178:181], v[220:223], v[54:57]
	v_mfma_f32_16x16x32_bf16 v[58:61], v[170:173], v[228:231], v[58:61]
	v_mfma_f32_16x16x32_bf16 v[50:53], v[178:181], v[228:231], v[50:53]
	s_nop 0
	s_barrier
	s_add_i32 s65, 0, 0x18000
	s_add_i32 s66, 0, 0x1c000
	v_add_u32_e32 v154, s65, v140
	v_add_u32_e32 v242, s65, v240
	v_add_u32_e32 v169, s66, v140
	v_add_u32_e32 v243, s66, v240
	ds_read_b128 v[142:145], v154
	ds_read_b128 v[146:149], v242
	ds_read_b128 v[150:153], v154 offset:2048
	ds_read_b128 v[154:157], v242 offset:2048
	ds_read_b128 v[162:165], v169
	ds_read_b128 v[170:173], v243
	ds_read_b128 v[174:177], v169 offset:2048
	ds_read_b128 v[178:181], v243 offset:2048
	s_add_u32 s52, s52, 0x80000
	s_addc_u32 s53, s53, 0
	s_mov_b32 m0, s84
	v_lshl_add_u64 v[234:235], s[52:53], 0, v[0:1]
	ds_read_b128 v[182:185], v141 offset:32768
	ds_read_b128 v[190:193], v241 offset:32768
	ds_read_b128 v[194:197], v141 offset:34816
	ds_read_b128 v[198:201], v241 offset:34816
	ds_read_b128 v[216:219], v141 offset:36864
	ds_read_b128 v[220:223], v241 offset:36864
	ds_read_b128 v[224:227], v141 offset:38912
	ds_read_b128 v[228:231], v241 offset:38912
	global_load_lds_dwordx4 v[234:235], off
	v_lshl_add_u64 v[234:235], s[52:53], 0, v[130:131]
	s_mov_b32 m0, s85
	s_nop 0
	global_load_lds_dwordx4 v[234:235], off
	s_waitcnt vmcnt(8)
	s_waitcnt lgkmcnt(0)
	s_barrier
	s_nop 0
	s_waitcnt lgkmcnt(0)
	v_mfma_f32_16x16x32_bf16 v[90:93], v[142:145], v[182:185], v[90:93]
	v_mfma_f32_16x16x32_bf16 v[74:77], v[150:153], v[182:185], v[74:77]
	v_mfma_f32_16x16x32_bf16 v[94:97], v[142:145], v[194:197], v[94:97]
	v_mfma_f32_16x16x32_bf16 v[78:81], v[150:153], v[194:197], v[78:81]
	v_mfma_f32_16x16x32_bf16 v[102:105], v[142:145], v[216:219], v[102:105]
	v_mfma_f32_16x16x32_bf16 v[98:101], v[150:153], v[216:219], v[98:101]
	v_mfma_f32_16x16x32_bf16 v[118:121], v[142:145], v[224:227], v[118:121]
	v_mfma_f32_16x16x32_bf16 v[106:109], v[150:153], v[224:227], v[106:109]
	v_mfma_f32_16x16x32_bf16 v[90:93], v[146:149], v[190:193], v[90:93]
	v_mfma_f32_16x16x32_bf16 v[74:77], v[154:157], v[190:193], v[74:77]
	v_mfma_f32_16x16x32_bf16 v[94:97], v[146:149], v[198:201], v[94:97]
	v_mfma_f32_16x16x32_bf16 v[78:81], v[154:157], v[198:201], v[78:81]
	v_mfma_f32_16x16x32_bf16 v[102:105], v[146:149], v[220:223], v[102:105]
	v_mfma_f32_16x16x32_bf16 v[98:101], v[154:157], v[220:223], v[98:101]
	v_mfma_f32_16x16x32_bf16 v[118:121], v[146:149], v[228:231], v[118:121]
	v_mfma_f32_16x16x32_bf16 v[106:109], v[154:157], v[228:231], v[106:109]
	s_nop 0
	s_nop 0
	v_mfma_f32_16x16x32_bf16 v[6:9], v[162:165], v[182:185], v[6:9]
	v_mfma_f32_16x16x32_bf16 v[2:5], v[174:177], v[182:185], v[2:5]
	v_mfma_f32_16x16x32_bf16 v[14:17], v[162:165], v[194:197], v[14:17]
	v_mfma_f32_16x16x32_bf16 v[10:13], v[174:177], v[194:197], v[10:13]
	v_mfma_f32_16x16x32_bf16 v[22:25], v[162:165], v[216:219], v[22:25]
	v_mfma_f32_16x16x32_bf16 v[18:21], v[174:177], v[216:219], v[18:21]
	v_mfma_f32_16x16x32_bf16 v[30:33], v[162:165], v[224:227], v[30:33]
	v_mfma_f32_16x16x32_bf16 v[26:29], v[174:177], v[224:227], v[26:29]
	v_mfma_f32_16x16x32_bf16 v[6:9], v[170:173], v[190:193], v[6:9]
	v_mfma_f32_16x16x32_bf16 v[2:5], v[178:181], v[190:193], v[2:5]
	v_mfma_f32_16x16x32_bf16 v[14:17], v[170:173], v[198:201], v[14:17]
	v_mfma_f32_16x16x32_bf16 v[10:13], v[178:181], v[198:201], v[10:13]
	v_mfma_f32_16x16x32_bf16 v[22:25], v[170:173], v[220:223], v[22:25]
	v_mfma_f32_16x16x32_bf16 v[18:21], v[178:181], v[220:223], v[18:21]
	v_mfma_f32_16x16x32_bf16 v[30:33], v[170:173], v[228:231], v[30:33]
	v_mfma_f32_16x16x32_bf16 v[26:29], v[178:181], v[228:231], v[26:29]
	s_nop 0
	s_barrier
	s_add_i32 s52, s65, s80
	v_lshl_add_u64 v[158:159], v[158:159], 0, s[20:21]
	s_mov_b32 m0, s52
	ds_read_b128 v[182:185], v141 offset:49152
	ds_read_b128 v[190:193], v241 offset:49152
	ds_read_b128 v[194:197], v141 offset:51200
	ds_read_b128 v[198:201], v241 offset:51200
	ds_read_b128 v[216:219], v141 offset:53248
	ds_read_b128 v[220:223], v241 offset:53248
	ds_read_b128 v[224:227], v141 offset:55296
	ds_read_b128 v[228:231], v241 offset:55296
	global_load_lds_dwordx4 v[158:159], off
	s_add_i32 m0, s52, 0x2000
	s_add_u32 s36, s36, 0x80080
	v_lshl_add_u64 v[158:159], v[166:167], 0, s[20:21]
	s_addc_u32 s37, s37, 0
	s_add_i32 s52, s66, s80
	global_load_lds_dwordx4 v[158:159], off
	v_lshl_add_u64 v[158:159], s[36:37], 0, v[0:1]
	s_mov_b32 m0, s52
	s_nop 0
	global_load_lds_dwordx4 v[158:159], off
	v_lshl_add_u64 v[158:159], s[36:37], 0, v[130:131]
	s_add_i32 m0, s52, 0x2000
	s_nop 0
	global_load_lds_dwordx4 v[158:159], off
	v_lshl_add_u64 v[158:159], v[202:203], 0, s[20:21]
	s_mov_b32 m0, s14
	s_nop 0
	global_load_lds_dwordx4 v[158:159], off
	v_lshl_add_u64 v[158:159], v[232:233], 0, s[20:21]
	s_mov_b32 m0, s15
	s_nop 0
	global_load_lds_dwordx4 v[158:159], off
	s_waitcnt vmcnt(8)
	s_waitcnt lgkmcnt(0)
	s_barrier
	s_nop 0
	s_waitcnt lgkmcnt(0)
	v_mfma_f32_16x16x32_bf16 v[126:129], v[142:145], v[182:185], v[126:129]
	v_mfma_f32_16x16x32_bf16 v[122:125], v[150:153], v[182:185], v[122:125]
	v_mfma_f32_16x16x32_bf16 v[114:117], v[142:145], v[194:197], v[114:117]
	v_mfma_f32_16x16x32_bf16 v[110:113], v[150:153], v[194:197], v[110:113]
	v_mfma_f32_16x16x32_bf16 v[86:89], v[142:145], v[216:219], v[86:89]
	v_mfma_f32_16x16x32_bf16 v[82:85], v[150:153], v[216:219], v[82:85]
	v_mfma_f32_16x16x32_bf16 v[70:73], v[142:145], v[224:227], v[70:73]
	v_mfma_f32_16x16x32_bf16 v[66:69], v[150:153], v[224:227], v[66:69]
	v_mfma_f32_16x16x32_bf16 v[126:129], v[146:149], v[190:193], v[126:129]
	v_mfma_f32_16x16x32_bf16 v[122:125], v[154:157], v[190:193], v[122:125]
	v_mfma_f32_16x16x32_bf16 v[114:117], v[146:149], v[198:201], v[114:117]
	v_mfma_f32_16x16x32_bf16 v[110:113], v[154:157], v[198:201], v[110:113]
	v_mfma_f32_16x16x32_bf16 v[86:89], v[146:149], v[220:223], v[86:89]
	v_mfma_f32_16x16x32_bf16 v[82:85], v[154:157], v[220:223], v[82:85]
	v_mfma_f32_16x16x32_bf16 v[70:73], v[146:149], v[228:231], v[70:73]
	v_mfma_f32_16x16x32_bf16 v[66:69], v[154:157], v[228:231], v[66:69]
	s_nop 0
	s_nop 0
	v_mfma_f32_16x16x32_bf16 v[38:41], v[162:165], v[182:185], v[38:41]
	v_mfma_f32_16x16x32_bf16 v[34:37], v[174:177], v[182:185], v[34:37]
	v_mfma_f32_16x16x32_bf16 v[46:49], v[162:165], v[194:197], v[46:49]
	v_mfma_f32_16x16x32_bf16 v[42:45], v[174:177], v[194:197], v[42:45]
	v_mfma_f32_16x16x32_bf16 v[62:65], v[162:165], v[216:219], v[62:65]
	v_mfma_f32_16x16x32_bf16 v[54:57], v[174:177], v[216:219], v[54:57]
	v_mfma_f32_16x16x32_bf16 v[58:61], v[162:165], v[224:227], v[58:61]
	v_mfma_f32_16x16x32_bf16 v[50:53], v[174:177], v[224:227], v[50:53]
	v_mfma_f32_16x16x32_bf16 v[38:41], v[170:173], v[190:193], v[38:41]
	v_mfma_f32_16x16x32_bf16 v[34:37], v[178:181], v[190:193], v[34:37]
	v_mfma_f32_16x16x32_bf16 v[46:49], v[170:173], v[198:201], v[46:49]
	v_mfma_f32_16x16x32_bf16 v[42:45], v[178:181], v[198:201], v[42:45]
	v_mfma_f32_16x16x32_bf16 v[62:65], v[170:173], v[220:223], v[62:65]
	v_mfma_f32_16x16x32_bf16 v[54:57], v[178:181], v[220:223], v[54:57]
	v_mfma_f32_16x16x32_bf16 v[58:61], v[170:173], v[228:231], v[58:61]
	v_mfma_f32_16x16x32_bf16 v[50:53], v[178:181], v[228:231], v[50:53]
	s_nop 0
	s_barrier
	s_add_i32 s64, s64, 2
	s_add_u32 s50, s50, 0x100
	s_addc_u32 s51, s51, 0
	s_cmp_gt_u32 s64, 29
	s_cbranch_scc0 .LBB0_62
	s_add_u32 s36, s23, 0xffffff00
	s_addc_u32 s37, s24, -1
	s_andn2_b64 vcc, exec, s[40:41]
	s_cbranch_vccnz .LBB0_65
	v_mov_b32_e32 v50, 0
	s_mov_b32 s0, s44
	s_mov_b32 s55, s46
	s_mov_b64 s[42:43], s[48:49]
	s_mov_b32 s25, s22
	v_mov_b32_e32 v51, v50
	v_mov_b32_e32 v52, v50
	v_mov_b32_e32 v53, v50
	v_mov_b32_e32 v58, v50
	v_mov_b32_e32 v59, v50
	v_mov_b32_e32 v60, v50
	v_mov_b32_e32 v61, v50
	v_mov_b32_e32 v54, v50
	v_mov_b32_e32 v55, v50
	v_mov_b32_e32 v56, v50
	v_mov_b32_e32 v57, v50
	v_mov_b32_e32 v62, v50
	v_mov_b32_e32 v63, v50
	v_mov_b32_e32 v64, v50
	v_mov_b32_e32 v65, v50
	v_mov_b32_e32 v42, v50
	v_mov_b32_e32 v43, v50
	v_mov_b32_e32 v44, v50
	v_mov_b32_e32 v45, v50
	v_mov_b32_e32 v46, v50
	v_mov_b32_e32 v47, v50
	v_mov_b32_e32 v48, v50
	v_mov_b32_e32 v49, v50
	v_mov_b32_e32 v34, v50
	v_mov_b32_e32 v35, v50
	v_mov_b32_e32 v36, v50
	v_mov_b32_e32 v37, v50
	v_mov_b32_e32 v38, v50
	v_mov_b32_e32 v39, v50
	v_mov_b32_e32 v40, v50
	v_mov_b32_e32 v41, v50
	v_mov_b32_e32 v66, v50
	v_mov_b32_e32 v67, v50
	v_mov_b32_e32 v68, v50
	v_mov_b32_e32 v69, v50
	v_mov_b32_e32 v70, v50
	v_mov_b32_e32 v71, v50
	v_mov_b32_e32 v72, v50
	v_mov_b32_e32 v73, v50
	v_mov_b32_e32 v82, v50
	v_mov_b32_e32 v83, v50
	v_mov_b32_e32 v84, v50
	v_mov_b32_e32 v85, v50
	v_mov_b32_e32 v86, v50
	v_mov_b32_e32 v87, v50
	v_mov_b32_e32 v88, v50
	v_mov_b32_e32 v89, v50
	v_mov_b32_e32 v110, v50
	v_mov_b32_e32 v111, v50
	v_mov_b32_e32 v112, v50
	v_mov_b32_e32 v113, v50
	v_mov_b32_e32 v114, v50
	v_mov_b32_e32 v115, v50
	v_mov_b32_e32 v116, v50
	v_mov_b32_e32 v117, v50
	v_mov_b32_e32 v122, v50
	v_mov_b32_e32 v123, v50
	v_mov_b32_e32 v124, v50
	v_mov_b32_e32 v125, v50
	v_mov_b32_e32 v126, v50
	v_mov_b32_e32 v127, v50
	v_mov_b32_e32 v128, v50
	v_mov_b32_e32 v129, v50
	v_mov_b32_e32 v26, v50
	v_mov_b32_e32 v27, v50
	v_mov_b32_e32 v28, v50
	v_mov_b32_e32 v29, v50
	v_mov_b32_e32 v30, v50
	v_mov_b32_e32 v31, v50
	v_mov_b32_e32 v32, v50
	v_mov_b32_e32 v33, v50
	v_mov_b32_e32 v18, v50
	v_mov_b32_e32 v19, v50
	v_mov_b32_e32 v20, v50
	v_mov_b32_e32 v21, v50
	v_mov_b32_e32 v22, v50
	v_mov_b32_e32 v23, v50
	v_mov_b32_e32 v24, v50
	v_mov_b32_e32 v25, v50
	v_mov_b32_e32 v10, v50
	v_mov_b32_e32 v11, v50
	v_mov_b32_e32 v12, v50
	v_mov_b32_e32 v13, v50
	v_mov_b32_e32 v14, v50
	v_mov_b32_e32 v15, v50
	v_mov_b32_e32 v16, v50
	v_mov_b32_e32 v17, v50
	v_mov_b32_e32 v2, v50
	v_mov_b32_e32 v3, v50
	v_mov_b32_e32 v4, v50
	v_mov_b32_e32 v5, v50
	v_mov_b32_e32 v6, v50
	v_mov_b32_e32 v7, v50
	v_mov_b32_e32 v8, v50
	v_mov_b32_e32 v9, v50
	v_mov_b32_e32 v106, v50
	v_mov_b32_e32 v107, v50
	v_mov_b32_e32 v108, v50
	v_mov_b32_e32 v109, v50
	v_mov_b32_e32 v118, v50
	v_mov_b32_e32 v119, v50
	v_mov_b32_e32 v120, v50
	v_mov_b32_e32 v121, v50
	v_mov_b32_e32 v98, v50
	v_mov_b32_e32 v99, v50
	v_mov_b32_e32 v100, v50
	v_mov_b32_e32 v101, v50
	v_mov_b32_e32 v102, v50
	v_mov_b32_e32 v103, v50
	v_mov_b32_e32 v104, v50
	v_mov_b32_e32 v105, v50
	v_mov_b32_e32 v78, v50
	v_mov_b32_e32 v79, v50
	v_mov_b32_e32 v80, v50
	v_mov_b32_e32 v81, v50
	v_mov_b32_e32 v94, v50
	v_mov_b32_e32 v95, v50
	v_mov_b32_e32 v96, v50
	v_mov_b32_e32 v97, v50
	v_mov_b32_e32 v74, v50
	v_mov_b32_e32 v75, v50
	v_mov_b32_e32 v76, v50
	v_mov_b32_e32 v77, v50
	v_mov_b32_e32 v90, v50
	v_mov_b32_e32 v91, v50
	v_mov_b32_e32 v92, v50
	v_mov_b32_e32 v93, v50
	s_branch .LBB0_66

.LBB0_70:
	s_setprio 0
	s_add_i32 s14, s94, -7
	s_cmp_lt_u32 s14, -11
	v_mov_b32_e32 v0, s2
	s_movk_i32 s18, 0xffc0
	s_cselect_b64 s[14:15], -1, 0
	v_bfi_b32 v150, s18, v0, v160
	s_lshl_b32 s18, s55, 3
	s_add_i32 s18, s18, s0
	s_ashr_i32 s19, s18, 31
	s_lshl_b64 s[18:19], s[18:19], 17
	s_add_u32 s18, s10, s18
	s_addc_u32 s19, s11, s19
	s_add_u32 s42, s18, 0x1ce00000
	s_addc_u32 s43, s19, 0
	v_readlane_b32 s18, v238, 6
	v_readlane_b32 s19, v238, 7
	s_or_b64 s[18:19], s[14:15], s[18:19]
	s_xor_b64 s[36:37], s[18:19], -1
	v_mov_b32_e32 v136, 0
	s_and_b64 vcc, exec, s[36:37]
	v_ashrrev_i32_e32 v151, 31, v150
	v_mov_b32_e32 v137, 0
	v_mov_b32_e32 v138, 0
	v_mov_b32_e32 v139, 0
	s_mov_b64 s[84:85], s[72:73]
	s_mov_b32 s87, s75
	s_barrier
	s_lshl_b32 s14, s29, 5
	s_lshl_b32 s15, s0, 8
	s_or_b32 s14, s15, s14
	v_lshrrev_b32_e32 v0, 2, v160
	s_lshl_b32 s44, s55, 8
	v_and_or_b32 v152, v0, 12, s14
	s_add_i32 s14, s44, s81
	v_or_b32_e32 v154, s14, v161
	v_ashrrev_i32_e32 v153, 31, v152
	s_cbranch_vccnz .Lres_f32
	v_lshlrev_b32_e32 v158, 4, v150
	v_lshlrev_b32_e32 v159, 1, v152
	v_lshl_add_u32 v0, v154, 12, v159
	v_add_u32_e32 v159, 0x2000, v158
	v_readlane_b32 s6, v236, 43
	v_readlane_b32 s7, v236, 44
	s_mov_b64 s[36:37], s[42:43]
	s_mov_b64 s[38:39], s[6:7]
	global_load_dwordx4 v[142:145], v158, s[36:37] nt
	global_load_dwordx4 v[146:149], v159, s[36:37] nt
	global_load_dwordx2 v[134:135], v0, s[38:39] nt
	global_load_dwordx2 v[136:137], v0, s[38:39] offset:32 nt
	global_load_dwordx2 v[154:155], v0, s[38:39] offset:256 nt
	global_load_dwordx2 v[156:157], v0, s[38:39] offset:288 nt
	s_add_u32 s36, s42, 0x4000
	s_addc_u32 s37, s43, 0
	s_add_u32 s38, s6, 0x10000
	s_addc_u32 s39, s7, 0
	global_load_dwordx4 v[170:173], v158, s[36:37] nt
	global_load_dwordx4 v[174:177], v159, s[36:37] nt
	global_load_dwordx2 v[178:179], v0, s[38:39] nt
	global_load_dwordx2 v[180:181], v0, s[38:39] offset:32 nt
	global_load_dwordx2 v[182:183], v0, s[38:39] offset:256 nt
	global_load_dwordx2 v[184:185], v0, s[38:39] offset:288 nt
	s_add_u32 s36, s42, 0x8000
	s_addc_u32 s37, s43, 0
	s_add_u32 s38, s6, 0x20000
	s_addc_u32 s39, s7, 0
	global_load_dwordx4 v[216:219], v158, s[36:37] nt
	global_load_dwordx4 v[220:223], v159, s[36:37] nt
	global_load_dwordx2 v[224:225], v0, s[38:39] nt
	global_load_dwordx2 v[226:227], v0, s[38:39] offset:32 nt
	global_load_dwordx2 v[228:229], v0, s[38:39] offset:256 nt
	global_load_dwordx2 v[230:231], v0, s[38:39] offset:288 nt
	s_add_u32 s36, s42, 0xc000
	s_addc_u32 s37, s43, 0
	s_add_u32 s38, s6, 0x30000
	s_addc_u32 s39, s7, 0
	global_load_dwordx4 v[190:193], v158, s[36:37] nt
	global_load_dwordx4 v[194:197], v159, s[36:37] nt
	global_load_dwordx2 v[198:199], v0, s[38:39] nt
	global_load_dwordx2 v[200:201], v0, s[38:39] offset:32 nt
	global_load_dwordx2 v[162:163], v0, s[38:39] offset:256 nt
	global_load_dwordx2 v[164:165], v0, s[38:39] offset:288 nt
	s_waitcnt vmcnt(18)
	v_lshlrev_b32_e32 v130, 16, v142
	v_and_b32_e32 v131, 0xffff0000, v142
	v_lshlrev_b32_e32 v132, 16, v143
	v_and_b32_e32 v133, 0xffff0000, v143
	v_lshlrev_b32_e32 v138, 16, v134
	v_and_b32_e32 v139, 0xffff0000, v134
	v_lshlrev_b32_e32 v140, 16, v135
	v_and_b32_e32 v141, 0xffff0000, v135
	v_pk_add_f32 v[130:131], v[130:131], v[138:139]
	v_pk_add_f32 v[132:133], v[132:133], v[140:141]
	v_pk_fma_f32 v[90:91], v[130:131], s[86:87], v[90:91] op_sel_hi:[1,0,1]
	v_pk_fma_f32 v[92:93], v[132:133], s[86:87], v[92:93] op_sel_hi:[1,0,1]
	v_lshlrev_b32_e32 v130, 16, v144
	v_and_b32_e32 v131, 0xffff0000, v144
	v_lshlrev_b32_e32 v132, 16, v145
	v_and_b32_e32 v133, 0xffff0000, v145
	v_lshlrev_b32_e32 v138, 16, v136
	v_and_b32_e32 v139, 0xffff0000, v136
	v_lshlrev_b32_e32 v140, 16, v137
	v_and_b32_e32 v141, 0xffff0000, v137
	v_pk_add_f32 v[130:131], v[130:131], v[138:139]
	v_pk_add_f32 v[132:133], v[132:133], v[140:141]
	v_pk_fma_f32 v[74:75], v[130:131], s[86:87], v[74:75] op_sel_hi:[1,0,1]
	v_pk_fma_f32 v[76:77], v[132:133], s[86:87], v[76:77] op_sel_hi:[1,0,1]
	v_lshlrev_b32_e32 v130, 16, v146
	v_and_b32_e32 v131, 0xffff0000, v146
	v_lshlrev_b32_e32 v132, 16, v147
	v_and_b32_e32 v133, 0xffff0000, v147
	v_lshlrev_b32_e32 v138, 16, v154
	v_and_b32_e32 v139, 0xffff0000, v154
	v_lshlrev_b32_e32 v140, 16, v155
	v_and_b32_e32 v141, 0xffff0000, v155
	v_pk_add_f32 v[130:131], v[130:131], v[138:139]
	v_pk_add_f32 v[132:133], v[132:133], v[140:141]
	v_pk_fma_f32 v[6:7], v[130:131], s[86:87], v[6:7] op_sel_hi:[1,0,1]
	v_pk_fma_f32 v[8:9], v[132:133], s[86:87], v[8:9] op_sel_hi:[1,0,1]
	v_lshlrev_b32_e32 v130, 16, v148
	v_and_b32_e32 v131, 0xffff0000, v148
	v_lshlrev_b32_e32 v132, 16, v149
	v_and_b32_e32 v133, 0xffff0000, v149
	v_lshlrev_b32_e32 v138, 16, v156
	v_and_b32_e32 v139, 0xffff0000, v156
	v_lshlrev_b32_e32 v140, 16, v157
	v_and_b32_e32 v141, 0xffff0000, v157
	v_pk_add_f32 v[130:131], v[130:131], v[138:139]
	v_pk_add_f32 v[132:133], v[132:133], v[140:141]
	v_pk_fma_f32 v[2:3], v[130:131], s[86:87], v[2:3] op_sel_hi:[1,0,1]
	v_pk_fma_f32 v[4:5], v[132:133], s[86:87], v[4:5] op_sel_hi:[1,0,1]
	s_add_u32 s36, s42, 0x10000
	s_addc_u32 s37, s43, 0
	s_add_u32 s38, s6, 0x80000
	s_addc_u32 s39, s7, 0
	global_load_dwordx4 v[142:145], v158, s[36:37] nt
	global_load_dwordx4 v[146:149], v159, s[36:37] nt
	global_load_dwordx2 v[134:135], v0, s[38:39] nt
	global_load_dwordx2 v[136:137], v0, s[38:39] offset:32 nt
	global_load_dwordx2 v[154:155], v0, s[38:39] offset:256 nt
	global_load_dwordx2 v[156:157], v0, s[38:39] offset:288 nt
	s_waitcnt vmcnt(18)
	v_lshlrev_b32_e32 v130, 16, v170
	v_and_b32_e32 v131, 0xffff0000, v170
	v_lshlrev_b32_e32 v132, 16, v171
	v_and_b32_e32 v133, 0xffff0000, v171
	v_lshlrev_b32_e32 v138, 16, v178
	v_and_b32_e32 v139, 0xffff0000, v178
	v_lshlrev_b32_e32 v140, 16, v179
	v_and_b32_e32 v141, 0xffff0000, v179
	v_pk_add_f32 v[130:131], v[130:131], v[138:139]
	v_pk_add_f32 v[132:133], v[132:133], v[140:141]
	v_pk_fma_f32 v[94:95], v[130:131], s[86:87], v[94:95] op_sel_hi:[1,0,1]
	v_pk_fma_f32 v[96:97], v[132:133], s[86:87], v[96:97] op_sel_hi:[1,0,1]
	v_lshlrev_b32_e32 v130, 16, v172
	v_and_b32_e32 v131, 0xffff0000, v172
	v_lshlrev_b32_e32 v132, 16, v173
	v_and_b32_e32 v133, 0xffff0000, v173
	v_lshlrev_b32_e32 v138, 16, v180
	v_and_b32_e32 v139, 0xffff0000, v180
	v_lshlrev_b32_e32 v140, 16, v181
	v_and_b32_e32 v141, 0xffff0000, v181
	v_pk_add_f32 v[130:131], v[130:131], v[138:139]
	v_pk_add_f32 v[132:133], v[132:133], v[140:141]
	v_pk_fma_f32 v[78:79], v[130:131], s[86:87], v[78:79] op_sel_hi:[1,0,1]
	v_pk_fma_f32 v[80:81], v[132:133], s[86:87], v[80:81] op_sel_hi:[1,0,1]
	v_lshlrev_b32_e32 v130, 16, v174
	v_and_b32_e32 v131, 0xffff0000, v174
	v_lshlrev_b32_e32 v132, 16, v175
	v_and_b32_e32 v133, 0xffff0000, v175
	v_lshlrev_b32_e32 v138, 16, v182
	v_and_b32_e32 v139, 0xffff0000, v182
	v_lshlrev_b32_e32 v140, 16, v183
	v_and_b32_e32 v141, 0xffff0000, v183
	v_pk_add_f32 v[130:131], v[130:131], v[138:139]
	v_pk_add_f32 v[132:133], v[132:133], v[140:141]
	v_pk_fma_f32 v[14:15], v[130:131], s[86:87], v[14:15] op_sel_hi:[1,0,1]
	v_pk_fma_f32 v[16:17], v[132:133], s[86:87], v[16:17] op_sel_hi:[1,0,1]
	v_lshlrev_b32_e32 v130, 16, v176
	v_and_b32_e32 v131, 0xffff0000, v176
	v_lshlrev_b32_e32 v132, 16, v177
	v_and_b32_e32 v133, 0xffff0000, v177
	v_lshlrev_b32_e32 v138, 16, v184
	v_and_b32_e32 v139, 0xffff0000, v184
	v_lshlrev_b32_e32 v140, 16, v185
	v_and_b32_e32 v141, 0xffff0000, v185
	v_pk_add_f32 v[130:131], v[130:131], v[138:139]
	v_pk_add_f32 v[132:133], v[132:133], v[140:141]
	v_pk_fma_f32 v[10:11], v[130:131], s[86:87], v[10:11] op_sel_hi:[1,0,1]
	v_pk_fma_f32 v[12:13], v[132:133], s[86:87], v[12:13] op_sel_hi:[1,0,1]
	s_add_u32 s36, s42, 0x14000
	s_addc_u32 s37, s43, 0
	s_add_u32 s38, s6, 0x90000
	s_addc_u32 s39, s7, 0
	global_load_dwordx4 v[170:173], v158, s[36:37] nt
	global_load_dwordx4 v[174:177], v159, s[36:37] nt
	global_load_dwordx2 v[178:179], v0, s[38:39] nt
	global_load_dwordx2 v[180:181], v0, s[38:39] offset:32 nt
	global_load_dwordx2 v[182:183], v0, s[38:39] offset:256 nt
	global_load_dwordx2 v[184:185], v0, s[38:39] offset:288 nt
	s_waitcnt vmcnt(18)
	v_lshlrev_b32_e32 v130, 16, v216
	v_and_b32_e32 v131, 0xffff0000, v216
	v_lshlrev_b32_e32 v132, 16, v217
	v_and_b32_e32 v133, 0xffff0000, v217
	v_lshlrev_b32_e32 v138, 16, v224
	v_and_b32_e32 v139, 0xffff0000, v224
	v_lshlrev_b32_e32 v140, 16, v225
	v_and_b32_e32 v141, 0xffff0000, v225
	v_pk_add_f32 v[130:131], v[130:131], v[138:139]
	v_pk_add_f32 v[132:133], v[132:133], v[140:141]
	v_pk_fma_f32 v[102:103], v[130:131], s[86:87], v[102:103] op_sel_hi:[1,0,1]
	v_pk_fma_f32 v[104:105], v[132:133], s[86:87], v[104:105] op_sel_hi:[1,0,1]
	v_lshlrev_b32_e32 v130, 16, v218
	v_and_b32_e32 v131, 0xffff0000, v218
	v_lshlrev_b32_e32 v132, 16, v219
	v_and_b32_e32 v133, 0xffff0000, v219
	v_lshlrev_b32_e32 v138, 16, v226
	v_and_b32_e32 v139, 0xffff0000, v226
	v_lshlrev_b32_e32 v140, 16, v227
	v_and_b32_e32 v141, 0xffff0000, v227
	v_pk_add_f32 v[130:131], v[130:131], v[138:139]
	v_pk_add_f32 v[132:133], v[132:133], v[140:141]
	v_pk_fma_f32 v[98:99], v[130:131], s[86:87], v[98:99] op_sel_hi:[1,0,1]
	v_pk_fma_f32 v[100:101], v[132:133], s[86:87], v[100:101] op_sel_hi:[1,0,1]
	v_lshlrev_b32_e32 v130, 16, v220
	v_and_b32_e32 v131, 0xffff0000, v220
	v_lshlrev_b32_e32 v132, 16, v221
	v_and_b32_e32 v133, 0xffff0000, v221
	v_lshlrev_b32_e32 v138, 16, v228
	v_and_b32_e32 v139, 0xffff0000, v228
	v_lshlrev_b32_e32 v140, 16, v229
	v_and_b32_e32 v141, 0xffff0000, v229
	v_pk_add_f32 v[130:131], v[130:131], v[138:139]
	v_pk_add_f32 v[132:133], v[132:133], v[140:141]
	v_pk_fma_f32 v[22:23], v[130:131], s[86:87], v[22:23] op_sel_hi:[1,0,1]
	v_pk_fma_f32 v[24:25], v[132:133], s[86:87], v[24:25] op_sel_hi:[1,0,1]
	v_lshlrev_b32_e32 v130, 16, v222
	v_and_b32_e32 v131, 0xffff0000, v222
	v_lshlrev_b32_e32 v132, 16, v223
	v_and_b32_e32 v133, 0xffff0000, v223
	v_lshlrev_b32_e32 v138, 16, v230
	v_and_b32_e32 v139, 0xffff0000, v230
	v_lshlrev_b32_e32 v140, 16, v231
	v_and_b32_e32 v141, 0xffff0000, v231
	v_pk_add_f32 v[130:131], v[130:131], v[138:139]
	v_pk_add_f32 v[132:133], v[132:133], v[140:141]
	v_pk_fma_f32 v[18:19], v[130:131], s[86:87], v[18:19] op_sel_hi:[1,0,1]
	v_pk_fma_f32 v[20:21], v[132:133], s[86:87], v[20:21] op_sel_hi:[1,0,1]
	s_add_u32 s36, s42, 0x18000
	s_addc_u32 s37, s43, 0
	s_add_u32 s38, s6, 0xa0000
	s_addc_u32 s39, s7, 0
	global_load_dwordx4 v[216:219], v158, s[36:37] nt
	global_load_dwordx4 v[220:223], v159, s[36:37] nt
	global_load_dwordx2 v[224:225], v0, s[38:39] nt
	global_load_dwordx2 v[226:227], v0, s[38:39] offset:32 nt
	global_load_dwordx2 v[228:229], v0, s[38:39] offset:256 nt
	global_load_dwordx2 v[230:231], v0, s[38:39] offset:288 nt
	s_waitcnt vmcnt(18)
	v_lshlrev_b32_e32 v130, 16, v190
	v_and_b32_e32 v131, 0xffff0000, v190
	v_lshlrev_b32_e32 v132, 16, v191
	v_and_b32_e32 v133, 0xffff0000, v191
	v_lshlrev_b32_e32 v138, 16, v198
	v_and_b32_e32 v139, 0xffff0000, v198
	v_lshlrev_b32_e32 v140, 16, v199
	v_and_b32_e32 v141, 0xffff0000, v199
	v_pk_add_f32 v[130:131], v[130:131], v[138:139]
	v_pk_add_f32 v[132:133], v[132:133], v[140:141]
	v_pk_fma_f32 v[118:119], v[130:131], s[86:87], v[118:119] op_sel_hi:[1,0,1]
	v_pk_fma_f32 v[120:121], v[132:133], s[86:87], v[120:121] op_sel_hi:[1,0,1]
	v_lshlrev_b32_e32 v130, 16, v192
	v_and_b32_e32 v131, 0xffff0000, v192
	v_lshlrev_b32_e32 v132, 16, v193
	v_and_b32_e32 v133, 0xffff0000, v193
	v_lshlrev_b32_e32 v138, 16, v200
	v_and_b32_e32 v139, 0xffff0000, v200
	v_lshlrev_b32_e32 v140, 16, v201
	v_and_b32_e32 v141, 0xffff0000, v201
	v_pk_add_f32 v[130:131], v[130:131], v[138:139]
	v_pk_add_f32 v[132:133], v[132:133], v[140:141]
	v_pk_fma_f32 v[106:107], v[130:131], s[86:87], v[106:107] op_sel_hi:[1,0,1]
	v_pk_fma_f32 v[108:109], v[132:133], s[86:87], v[108:109] op_sel_hi:[1,0,1]
	v_lshlrev_b32_e32 v130, 16, v194
	v_and_b32_e32 v131, 0xffff0000, v194
	v_lshlrev_b32_e32 v132, 16, v195
	v_and_b32_e32 v133, 0xffff0000, v195
	v_lshlrev_b32_e32 v138, 16, v162
	v_and_b32_e32 v139, 0xffff0000, v162
	v_lshlrev_b32_e32 v140, 16, v163
	v_and_b32_e32 v141, 0xffff0000, v163
	v_pk_add_f32 v[130:131], v[130:131], v[138:139]
	v_pk_add_f32 v[132:133], v[132:133], v[140:141]
	v_pk_fma_f32 v[30:31], v[130:131], s[86:87], v[30:31] op_sel_hi:[1,0,1]
	v_pk_fma_f32 v[32:33], v[132:133], s[86:87], v[32:33] op_sel_hi:[1,0,1]
	v_lshlrev_b32_e32 v130, 16, v196
	v_and_b32_e32 v131, 0xffff0000, v196
	v_lshlrev_b32_e32 v132, 16, v197
	v_and_b32_e32 v133, 0xffff0000, v197
	v_lshlrev_b32_e32 v138, 16, v164
	v_and_b32_e32 v139, 0xffff0000, v164
	v_lshlrev_b32_e32 v140, 16, v165
	v_and_b32_e32 v141, 0xffff0000, v165
	v_pk_add_f32 v[130:131], v[130:131], v[138:139]
	v_pk_add_f32 v[132:133], v[132:133], v[140:141]
	v_pk_fma_f32 v[26:27], v[130:131], s[86:87], v[26:27] op_sel_hi:[1,0,1]
	v_pk_fma_f32 v[28:29], v[132:133], s[86:87], v[28:29] op_sel_hi:[1,0,1]
	s_add_u32 s36, s42, 0x1c000
	s_addc_u32 s37, s43, 0
	s_add_u32 s38, s6, 0xb0000
	s_addc_u32 s39, s7, 0
	global_load_dwordx4 v[190:193], v158, s[36:37] nt
	global_load_dwordx4 v[194:197], v159, s[36:37] nt
	global_load_dwordx2 v[198:199], v0, s[38:39] nt
	global_load_dwordx2 v[200:201], v0, s[38:39] offset:32 nt
	global_load_dwordx2 v[162:163], v0, s[38:39] offset:256 nt
	global_load_dwordx2 v[164:165], v0, s[38:39] offset:288 nt
	s_waitcnt vmcnt(18)
	v_lshlrev_b32_e32 v130, 16, v142
	v_and_b32_e32 v131, 0xffff0000, v142
	v_lshlrev_b32_e32 v132, 16, v143
	v_and_b32_e32 v133, 0xffff0000, v143
	v_lshlrev_b32_e32 v138, 16, v134
	v_and_b32_e32 v139, 0xffff0000, v134
	v_lshlrev_b32_e32 v140, 16, v135
	v_and_b32_e32 v141, 0xffff0000, v135
	v_pk_add_f32 v[130:131], v[130:131], v[138:139]
	v_pk_add_f32 v[132:133], v[132:133], v[140:141]
	v_pk_fma_f32 v[126:127], v[130:131], s[86:87], v[126:127] op_sel_hi:[1,0,1]
	v_pk_fma_f32 v[128:129], v[132:133], s[86:87], v[128:129] op_sel_hi:[1,0,1]
	v_lshlrev_b32_e32 v130, 16, v144
	v_and_b32_e32 v131, 0xffff0000, v144
	v_lshlrev_b32_e32 v132, 16, v145
	v_and_b32_e32 v133, 0xffff0000, v145
	v_lshlrev_b32_e32 v138, 16, v136
	v_and_b32_e32 v139, 0xffff0000, v136
	v_lshlrev_b32_e32 v140, 16, v137
	v_and_b32_e32 v141, 0xffff0000, v137
	v_pk_add_f32 v[130:131], v[130:131], v[138:139]
	v_pk_add_f32 v[132:133], v[132:133], v[140:141]
	v_pk_fma_f32 v[122:123], v[130:131], s[86:87], v[122:123] op_sel_hi:[1,0,1]
	v_pk_fma_f32 v[124:125], v[132:133], s[86:87], v[124:125] op_sel_hi:[1,0,1]
	v_lshlrev_b32_e32 v130, 16, v146
	v_and_b32_e32 v131, 0xffff0000, v146
	v_lshlrev_b32_e32 v132, 16, v147
	v_and_b32_e32 v133, 0xffff0000, v147
	v_lshlrev_b32_e32 v138, 16, v154
	v_and_b32_e32 v139, 0xffff0000, v154
	v_lshlrev_b32_e32 v140, 16, v155
	v_and_b32_e32 v141, 0xffff0000, v155
	v_pk_add_f32 v[130:131], v[130:131], v[138:139]
	v_pk_add_f32 v[132:133], v[132:133], v[140:141]
	v_pk_fma_f32 v[38:39], v[130:131], s[86:87], v[38:39] op_sel_hi:[1,0,1]
	v_pk_fma_f32 v[40:41], v[132:133], s[86:87], v[40:41] op_sel_hi:[1,0,1]
	v_lshlrev_b32_e32 v130, 16, v148
	v_and_b32_e32 v131, 0xffff0000, v148
	v_lshlrev_b32_e32 v132, 16, v149
	v_and_b32_e32 v133, 0xffff0000, v149
	v_lshlrev_b32_e32 v138, 16, v156
	v_and_b32_e32 v139, 0xffff0000, v156
	v_lshlrev_b32_e32 v140, 16, v157
	v_and_b32_e32 v141, 0xffff0000, v157
	v_pk_add_f32 v[130:131], v[130:131], v[138:139]
	v_pk_add_f32 v[132:133], v[132:133], v[140:141]
	v_pk_fma_f32 v[34:35], v[130:131], s[86:87], v[34:35] op_sel_hi:[1,0,1]
	v_pk_fma_f32 v[36:37], v[132:133], s[86:87], v[36:37] op_sel_hi:[1,0,1]
	s_waitcnt vmcnt(12)
	v_lshlrev_b32_e32 v130, 16, v170
	v_and_b32_e32 v131, 0xffff0000, v170
	v_lshlrev_b32_e32 v132, 16, v171
	v_and_b32_e32 v133, 0xffff0000, v171
	v_lshlrev_b32_e32 v138, 16, v178
	v_and_b32_e32 v139, 0xffff0000, v178
	v_lshlrev_b32_e32 v140, 16, v179
	v_and_b32_e32 v141, 0xffff0000, v179
	v_pk_add_f32 v[130:131], v[130:131], v[138:139]
	v_pk_add_f32 v[132:133], v[132:133], v[140:141]
	v_pk_fma_f32 v[114:115], v[130:131], s[86:87], v[114:115] op_sel_hi:[1,0,1]
	v_pk_fma_f32 v[116:117], v[132:133], s[86:87], v[116:117] op_sel_hi:[1,0,1]
	v_lshlrev_b32_e32 v130, 16, v172
	v_and_b32_e32 v131, 0xffff0000, v172
	v_lshlrev_b32_e32 v132, 16, v173
	v_and_b32_e32 v133, 0xffff0000, v173
	v_lshlrev_b32_e32 v138, 16, v180
	v_and_b32_e32 v139, 0xffff0000, v180
	v_lshlrev_b32_e32 v140, 16, v181
	v_and_b32_e32 v141, 0xffff0000, v181
	v_pk_add_f32 v[130:131], v[130:131], v[138:139]
	v_pk_add_f32 v[132:133], v[132:133], v[140:141]
	v_pk_fma_f32 v[110:111], v[130:131], s[86:87], v[110:111] op_sel_hi:[1,0,1]
	v_pk_fma_f32 v[112:113], v[132:133], s[86:87], v[112:113] op_sel_hi:[1,0,1]
	v_lshlrev_b32_e32 v130, 16, v174
	v_and_b32_e32 v131, 0xffff0000, v174
	v_lshlrev_b32_e32 v132, 16, v175
	v_and_b32_e32 v133, 0xffff0000, v175
	v_lshlrev_b32_e32 v138, 16, v182
	v_and_b32_e32 v139, 0xffff0000, v182
	v_lshlrev_b32_e32 v140, 16, v183
	v_and_b32_e32 v141, 0xffff0000, v183
	v_pk_add_f32 v[130:131], v[130:131], v[138:139]
	v_pk_add_f32 v[132:133], v[132:133], v[140:141]
	v_pk_fma_f32 v[46:47], v[130:131], s[86:87], v[46:47] op_sel_hi:[1,0,1]
	v_pk_fma_f32 v[48:49], v[132:133], s[86:87], v[48:49] op_sel_hi:[1,0,1]
	v_lshlrev_b32_e32 v130, 16, v176
	v_and_b32_e32 v131, 0xffff0000, v176
	v_lshlrev_b32_e32 v132, 16, v177
	v_and_b32_e32 v133, 0xffff0000, v177
	v_lshlrev_b32_e32 v138, 16, v184
	v_and_b32_e32 v139, 0xffff0000, v184
	v_lshlrev_b32_e32 v140, 16, v185
	v_and_b32_e32 v141, 0xffff0000, v185
	v_pk_add_f32 v[130:131], v[130:131], v[138:139]
	v_pk_add_f32 v[132:133], v[132:133], v[140:141]
	v_pk_fma_f32 v[42:43], v[130:131], s[86:87], v[42:43] op_sel_hi:[1,0,1]
	v_pk_fma_f32 v[44:45], v[132:133], s[86:87], v[44:45] op_sel_hi:[1,0,1]
	s_waitcnt vmcnt(6)
	v_lshlrev_b32_e32 v130, 16, v216
	v_and_b32_e32 v131, 0xffff0000, v216
	v_lshlrev_b32_e32 v132, 16, v217
	v_and_b32_e32 v133, 0xffff0000, v217
	v_lshlrev_b32_e32 v138, 16, v224
	v_and_b32_e32 v139, 0xffff0000, v224
	v_lshlrev_b32_e32 v140, 16, v225
	v_and_b32_e32 v141, 0xffff0000, v225
	v_pk_add_f32 v[130:131], v[130:131], v[138:139]
	v_pk_add_f32 v[132:133], v[132:133], v[140:141]
	v_pk_fma_f32 v[86:87], v[130:131], s[86:87], v[86:87] op_sel_hi:[1,0,1]
	v_pk_fma_f32 v[88:89], v[132:133], s[86:87], v[88:89] op_sel_hi:[1,0,1]
	v_lshlrev_b32_e32 v130, 16, v218
	v_and_b32_e32 v131, 0xffff0000, v218
	v_lshlrev_b32_e32 v132, 16, v219
	v_and_b32_e32 v133, 0xffff0000, v219
	v_lshlrev_b32_e32 v138, 16, v226
	v_and_b32_e32 v139, 0xffff0000, v226
	v_lshlrev_b32_e32 v140, 16, v227
	v_and_b32_e32 v141, 0xffff0000, v227
	v_pk_add_f32 v[130:131], v[130:131], v[138:139]
	v_pk_add_f32 v[132:133], v[132:133], v[140:141]
	v_pk_fma_f32 v[82:83], v[130:131], s[86:87], v[82:83] op_sel_hi:[1,0,1]
	v_pk_fma_f32 v[84:85], v[132:133], s[86:87], v[84:85] op_sel_hi:[1,0,1]
	v_lshlrev_b32_e32 v130, 16, v220
	v_and_b32_e32 v131, 0xffff0000, v220
	v_lshlrev_b32_e32 v132, 16, v221
	v_and_b32_e32 v133, 0xffff0000, v221
	v_lshlrev_b32_e32 v138, 16, v228
	v_and_b32_e32 v139, 0xffff0000, v228
	v_lshlrev_b32_e32 v140, 16, v229
	v_and_b32_e32 v141, 0xffff0000, v229
	v_pk_add_f32 v[130:131], v[130:131], v[138:139]
	v_pk_add_f32 v[132:133], v[132:133], v[140:141]
	v_pk_fma_f32 v[62:63], v[130:131], s[86:87], v[62:63] op_sel_hi:[1,0,1]
	v_pk_fma_f32 v[64:65], v[132:133], s[86:87], v[64:65] op_sel_hi:[1,0,1]
	v_lshlrev_b32_e32 v130, 16, v222
	v_and_b32_e32 v131, 0xffff0000, v222
	v_lshlrev_b32_e32 v132, 16, v223
	v_and_b32_e32 v133, 0xffff0000, v223
	v_lshlrev_b32_e32 v138, 16, v230
	v_and_b32_e32 v139, 0xffff0000, v230
	v_lshlrev_b32_e32 v140, 16, v231
	v_and_b32_e32 v141, 0xffff0000, v231
	v_pk_add_f32 v[130:131], v[130:131], v[138:139]
	v_pk_add_f32 v[132:133], v[132:133], v[140:141]
	v_pk_fma_f32 v[54:55], v[130:131], s[86:87], v[54:55] op_sel_hi:[1,0,1]
	v_pk_fma_f32 v[56:57], v[132:133], s[86:87], v[56:57] op_sel_hi:[1,0,1]
	s_waitcnt vmcnt(0)
	v_lshlrev_b32_e32 v130, 16, v190
	v_and_b32_e32 v131, 0xffff0000, v190
	v_lshlrev_b32_e32 v132, 16, v191
	v_and_b32_e32 v133, 0xffff0000, v191
	v_lshlrev_b32_e32 v138, 16, v198
	v_and_b32_e32 v139, 0xffff0000, v198
	v_lshlrev_b32_e32 v140, 16, v199
	v_and_b32_e32 v141, 0xffff0000, v199
	v_pk_add_f32 v[130:131], v[130:131], v[138:139]
	v_pk_add_f32 v[132:133], v[132:133], v[140:141]
	v_pk_fma_f32 v[70:71], v[130:131], s[86:87], v[70:71] op_sel_hi:[1,0,1]
	v_pk_fma_f32 v[72:73], v[132:133], s[86:87], v[72:73] op_sel_hi:[1,0,1]
	v_lshlrev_b32_e32 v130, 16, v192
	v_and_b32_e32 v131, 0xffff0000, v192
	v_lshlrev_b32_e32 v132, 16, v193
	v_and_b32_e32 v133, 0xffff0000, v193
	v_lshlrev_b32_e32 v138, 16, v200
	v_and_b32_e32 v139, 0xffff0000, v200
	v_lshlrev_b32_e32 v140, 16, v201
	v_and_b32_e32 v141, 0xffff0000, v201
	v_pk_add_f32 v[130:131], v[130:131], v[138:139]
	v_pk_add_f32 v[132:133], v[132:133], v[140:141]
	v_pk_fma_f32 v[66:67], v[130:131], s[86:87], v[66:67] op_sel_hi:[1,0,1]
	v_pk_fma_f32 v[68:69], v[132:133], s[86:87], v[68:69] op_sel_hi:[1,0,1]
	v_lshlrev_b32_e32 v130, 16, v194
	v_and_b32_e32 v131, 0xffff0000, v194
	v_lshlrev_b32_e32 v132, 16, v195
	v_and_b32_e32 v133, 0xffff0000, v195
	v_lshlrev_b32_e32 v138, 16, v162
	v_and_b32_e32 v139, 0xffff0000, v162
	v_lshlrev_b32_e32 v140, 16, v163
	v_and_b32_e32 v141, 0xffff0000, v163
	v_pk_add_f32 v[130:131], v[130:131], v[138:139]
	v_pk_add_f32 v[132:133], v[132:133], v[140:141]
	v_pk_fma_f32 v[58:59], v[130:131], s[86:87], v[58:59] op_sel_hi:[1,0,1]
	v_pk_fma_f32 v[60:61], v[132:133], s[86:87], v[60:61] op_sel_hi:[1,0,1]
	v_lshlrev_b32_e32 v130, 16, v196
	v_and_b32_e32 v131, 0xffff0000, v196
	v_lshlrev_b32_e32 v132, 16, v197
	v_and_b32_e32 v133, 0xffff0000, v197
	v_lshlrev_b32_e32 v138, 16, v164
	v_and_b32_e32 v139, 0xffff0000, v164
	v_lshlrev_b32_e32 v140, 16, v165
	v_and_b32_e32 v141, 0xffff0000, v165
	v_pk_add_f32 v[130:131], v[130:131], v[138:139]
	v_pk_add_f32 v[132:133], v[132:133], v[140:141]
	v_pk_fma_f32 v[50:51], v[130:131], s[86:87], v[50:51] op_sel_hi:[1,0,1]
	v_pk_fma_f32 v[52:53], v[132:133], s[86:87], v[52:53] op_sel_hi:[1,0,1]
	s_branch .Lres_done

.LBB0_379:
	s_andn2_b64 vcc, exec, s[36:37]
	s_cbranch_vccnz .LBB0_400
	v_mov_b32_e32 v248, s14
	ds_read_b32 v248, v248 offset:1024
	v_mov_b32_e32 v252, s88
	v_mov_b32_e32 v253, s88
	v_mov_b32_e32 v254, s88
	v_mov_b32_e32 v255, s88
	s_waitcnt lgkmcnt(0)
	v_mul_u32_u24_e32 v218, 0x90, v5
	s_lshr_b32 s15, s15, 1
	v_mov_b32_e32 v5, v1
	v_lshl_add_u64 v[202:203], s[18:19], 0, v[4:5]
	s_and_b32 s18, s23, 32
	s_lshl_b32 s19, s15, 6
	v_mul_u32_u24_e32 v4, 0x110, v6
	s_or_b32 s18, s19, s18
	v_lshlrev_b32_e32 v7, 3, v7
	v_add3_u32 v225, s24, v4, v2
	v_mul_u32_u24_e32 v2, 0x90, v6
	s_addk_i32 s18, 0x1ff
	v_add3_u32 v226, s24, v2, v7
	v_add_u32_e32 v2, s18, v6
	v_sub_u32_e32 v2, v2, v216
	s_lshl_b32 s23, s25, 6
	s_add_i32 s41, s38, 0xfffffe40
	v_mov_b32_e32 v4, v1
	v_mul_u32_u24_e32 v217, 0x110, v3
	v_mul_u32_u24_e32 v219, 0x110, v9
	v_mul_u32_u24_e32 v220, 0x90, v11
	v_mul_u32_u24_e32 v221, 0x110, v10
	v_mul_u32_u24_e32 v222, 0x90, v12
	v_mul_u32_u24_e32 v223, 0x110, v8
	v_mul_u32_u24_e32 v224, 0x90, v13
	v_subrev_u32_e32 v227, s23, v2
	s_sub_i32 s18, s15, s25
	v_add_u32_e32 v228, s41, v8
	v_add_u32_e32 v229, s41, v10
	v_add_u32_e32 v230, s41, v9
	v_add_u32_e32 v231, s41, v3
	v_mov_b32_e32 v2, v1
	v_mov_b32_e32 v3, v1
	v_mov_b64_e32 v[8:9], v[4:5]
	v_mov_b64_e32 v[12:13], v[4:5]
	v_mov_b64_e32 v[16:17], v[4:5]
	v_mov_b64_e32 v[20:21], v[4:5]
	v_mov_b64_e32 v[24:25], v[4:5]
	v_mov_b64_e32 v[28:29], v[4:5]
	v_mov_b64_e32 v[32:33], v[4:5]
	v_mov_b64_e32 v[40:41], v[4:5]
	v_mov_b64_e32 v[44:45], v[4:5]
	v_mov_b64_e32 v[48:49], v[4:5]
	v_mov_b64_e32 v[52:53], v[4:5]
	v_mov_b64_e32 v[56:57], v[4:5]
	v_mov_b64_e32 v[60:61], v[4:5]
	v_mov_b64_e32 v[64:65], v[4:5]
	v_mov_b64_e32 v[84:85], v[4:5]
	v_mov_b64_e32 v[36:37], v[4:5]
	v_mov_b64_e32 v[128:129], v[4:5]
	s_or_b32 s22, s15, 8
	s_add_i32 s24, s18, 8
	s_add_i32 s25, s25, -1
	v_mov_b32_e32 v233, 0xf149f2ca
	v_mov_b64_e32 v[6:7], v[2:3]
	v_mov_b64_e32 v[10:11], v[2:3]
	v_mov_b64_e32 v[14:15], v[2:3]
	v_mov_b64_e32 v[18:19], v[2:3]
	v_mov_b64_e32 v[22:23], v[2:3]
	v_mov_b64_e32 v[26:27], v[2:3]
	v_mov_b64_e32 v[30:31], v[2:3]
	v_mov_b64_e32 v[38:39], v[2:3]
	v_mov_b64_e32 v[42:43], v[2:3]
	v_mov_b64_e32 v[46:47], v[2:3]
	v_mov_b64_e32 v[50:51], v[2:3]
	v_mov_b64_e32 v[54:55], v[2:3]
	v_mov_b64_e32 v[58:59], v[2:3]
	v_mov_b64_e32 v[62:63], v[2:3]
	v_mov_b64_e32 v[82:83], v[2:3]
	v_mov_b64_e32 v[34:35], v[2:3]
	v_mov_b64_e32 v[126:127], v[2:3]
	v_mov_b32_e32 v232, 0xf149f2ca
	s_cmp_lg_u32 s25, 8
	s_cselect_b64 s[18:19], -1, 0
	s_cmp_eq_u32 s25, 8
	s_cbranch_scc1 .LBB0_382

.LBB0_387:
	v_exp_f32_e32 v157, v201
	v_cvt_pk_bf16_f32 v158, v170, v171
	v_cvt_pk_bf16_f32 v159, v172, v173
	v_cvt_pk_bf16_f32 v160, v174, v175
	v_cvt_pk_bf16_f32 v161, v176, v177
	v_cvt_pk_bf16_f32 v154, v178, v179
	v_cvt_pk_bf16_f32 v155, v180, v181
	v_mfma_f32_16x16x32_bf16 v[126:129], v[252:255], v[158:161], v[126:129]
	v_cvt_pk_bf16_f32 v156, v182, v183
	v_cvt_pk_bf16_f32 v157, v184, v157
	s_andn2_b64 vcc, exec, s[38:39]
	s_mov_b64 s[36:37], -1
	v_mfma_f32_16x16x32_bf16 v[126:129], v[252:255], v[154:157], v[126:129]
	s_cbranch_vccz .LBB0_398
	s_andn2_b64 vcc, exec, s[36:37]
	s_cbranch_vccz .LBB0_399

.LBB0_391:
	v_exp_f32_e32 v149, v179
	v_cvt_pk_bf16_f32 v138, v162, v163
	v_cvt_pk_bf16_f32 v139, v164, v165
	v_cvt_pk_bf16_f32 v140, v170, v171
	v_cvt_pk_bf16_f32 v141, v172, v173
	v_cvt_pk_bf16_f32 v146, v166, v167
	v_cvt_pk_bf16_f32 v147, v168, v169
	v_mfma_f32_16x16x32_bf16 v[34:37], v[252:255], v[138:141], v[34:37]
	v_cvt_pk_bf16_f32 v148, v174, v175
	v_cvt_pk_bf16_f32 v149, v176, v149
	s_mul_i32 s36, s42, 0x4800
	s_mov_b32 s89, 0x800000
	v_mfma_f32_16x16x32_bf16 v[34:37], v[252:255], v[146:149], v[34:37]
	v_mov_b32_e32 v142, 0
	s_nop 0
	v_add3_u32 v162, v226, s36, v142
	v_add_u32_e32 v150, 0x8800, v162
	ds_read2_b64 v[142:145], v150 offset1:4
	ds_read2_b64 v[150:153], v150 offset0:8 offset1:12
	s_waitcnt lgkmcnt(1)
	v_mfma_f32_16x16x32_bf16 v[82:85], v[142:145], v[158:161], v[82:85]
	v_mfma_f32_16x16x32_bf16 v[30:33], v[142:145], v[138:141], v[30:33]
	s_waitcnt lgkmcnt(0)
	v_mfma_f32_16x16x32_bf16 v[82:85], v[150:153], v[154:157], v[82:85]
	v_mfma_f32_16x16x32_bf16 v[30:33], v[150:153], v[146:149], v[30:33]
	v_add_u32_e32 v150, 0x9000, v162
	ds_read2_b64 v[142:145], v150 offset0:32 offset1:36
	ds_read2_b64 v[150:153], v150 offset0:40 offset1:44
	s_waitcnt lgkmcnt(1)
	v_mfma_f32_16x16x32_bf16 v[62:65], v[142:145], v[158:161], v[62:65]
	v_mfma_f32_16x16x32_bf16 v[26:29], v[142:145], v[138:141], v[26:29]
	s_waitcnt lgkmcnt(0)
	v_mfma_f32_16x16x32_bf16 v[62:65], v[150:153], v[154:157], v[62:65]
	v_mfma_f32_16x16x32_bf16 v[26:29], v[150:153], v[146:149], v[26:29]
	v_add_u32_e32 v150, 0x9800, v162
	ds_read2_b64 v[142:145], v150 offset0:64 offset1:68
	ds_read2_b64 v[150:153], v150 offset0:72 offset1:76
	s_waitcnt lgkmcnt(1)
	v_mfma_f32_16x16x32_bf16 v[58:61], v[142:145], v[158:161], v[58:61]
	v_mfma_f32_16x16x32_bf16 v[22:25], v[142:145], v[138:141], v[22:25]
	s_waitcnt lgkmcnt(0)
	v_mfma_f32_16x16x32_bf16 v[58:61], v[150:153], v[154:157], v[58:61]
	v_mfma_f32_16x16x32_bf16 v[22:25], v[150:153], v[146:149], v[22:25]
	v_add_u32_e32 v150, 0xa000, v162
	ds_read2_b64 v[142:145], v150 offset0:96 offset1:100
	ds_read2_b64 v[150:153], v150 offset0:104 offset1:108
	s_waitcnt lgkmcnt(1)
	v_mfma_f32_16x16x32_bf16 v[54:57], v[142:145], v[158:161], v[54:57]
	v_mfma_f32_16x16x32_bf16 v[18:21], v[142:145], v[138:141], v[18:21]
	s_waitcnt lgkmcnt(0)
	v_mfma_f32_16x16x32_bf16 v[54:57], v[150:153], v[154:157], v[54:57]
	v_mfma_f32_16x16x32_bf16 v[18:21], v[150:153], v[146:149], v[18:21]
	v_add_u32_e32 v150, 0xa800, v162
	ds_read2_b64 v[142:145], v150 offset0:128 offset1:132
	ds_read2_b64 v[150:153], v150 offset0:136 offset1:140
	s_waitcnt lgkmcnt(1)
	v_mfma_f32_16x16x32_bf16 v[50:53], v[142:145], v[158:161], v[50:53]
	v_mfma_f32_16x16x32_bf16 v[14:17], v[142:145], v[138:141], v[14:17]
	s_waitcnt lgkmcnt(0)
	v_mfma_f32_16x16x32_bf16 v[50:53], v[150:153], v[154:157], v[50:53]
	v_mfma_f32_16x16x32_bf16 v[14:17], v[150:153], v[146:149], v[14:17]
	v_add_u32_e32 v150, 0xb000, v162
	ds_read2_b64 v[142:145], v150 offset0:160 offset1:164
	ds_read2_b64 v[150:153], v150 offset0:168 offset1:172
	s_waitcnt lgkmcnt(1)
	v_mfma_f32_16x16x32_bf16 v[46:49], v[142:145], v[158:161], v[46:49]
	v_mfma_f32_16x16x32_bf16 v[10:13], v[142:145], v[138:141], v[10:13]
	s_waitcnt lgkmcnt(0)
	v_mfma_f32_16x16x32_bf16 v[46:49], v[150:153], v[154:157], v[46:49]
	v_mfma_f32_16x16x32_bf16 v[10:13], v[150:153], v[146:149], v[10:13]
	v_add_u32_e32 v150, 0xb800, v162
	ds_read2_b64 v[142:145], v150 offset0:192 offset1:196
	ds_read2_b64 v[150:153], v150 offset0:200 offset1:204
	s_waitcnt lgkmcnt(1)
	v_mfma_f32_16x16x32_bf16 v[42:45], v[142:145], v[158:161], v[42:45]
	v_mfma_f32_16x16x32_bf16 v[6:9], v[142:145], v[138:141], v[6:9]
	s_waitcnt lgkmcnt(0)
	v_mfma_f32_16x16x32_bf16 v[42:45], v[150:153], v[154:157], v[42:45]
	v_mfma_f32_16x16x32_bf16 v[6:9], v[150:153], v[146:149], v[6:9]
	v_add_u32_e32 v150, 0xc000, v162
	ds_read2_b64 v[142:145], v150 offset0:224 offset1:228
	ds_read2_b64 v[150:153], v150 offset0:232 offset1:236
	s_waitcnt lgkmcnt(1)
	v_mfma_f32_16x16x32_bf16 v[38:41], v[142:145], v[158:161], v[38:41]
	v_mfma_f32_16x16x32_bf16 v[2:5], v[142:145], v[138:141], v[2:5]
	s_waitcnt lgkmcnt(0)
	v_mfma_f32_16x16x32_bf16 v[38:41], v[150:153], v[154:157], v[38:41]
	v_mfma_f32_16x16x32_bf16 v[2:5], v[150:153], v[146:149], v[2:5]
	s_andn2_b64 vcc, exec, s[18:19]
	s_cbranch_vccz .LBB0_393
	s_branch .LBB0_394

.LBB0_397:
	v_max3_f32 v170, v154, v155, v156
	v_max3_f32 v171, v157, v158, v159
	v_max3_f32 v172, v160, v161, v162
	v_max3_f32 v170, v170, v171, v172
	v_max3_f32 v171, v163, v164, v165
	v_max3_f32 v172, v166, v167, v168
	v_max3_f32 v171, v171, v172, v169
	v_max_f32_e32 v170, v170, v171
	v_mov_b32_e32 v171, v170
	s_nop 1
	v_permlane16_swap_b32_e32 v171, v170
	v_max_f32_e32 v170, v170, v171
	v_mov_b32_e32 v171, v170
	s_nop 1
	v_permlane32_swap_b32_e32 v171, v170
	v_max_f32_e32 v170, v170, v171
	v_fmamk_f32 v170, v170, 0x3e0293ee, v248
	v_max_f32_e32 v197, v233, v170
	v_sub_f32_e32 v201, v248, v197
	v_fmamk_f32 v154, v154, 0x3e0293ee, v201
	v_exp_f32_e32 v170, v154
	v_fmamk_f32 v154, v155, 0x3e0293ee, v201
	v_exp_f32_e32 v171, v154
	v_fmamk_f32 v154, v156, 0x3e0293ee, v201
	v_exp_f32_e32 v172, v154
	v_fmamk_f32 v154, v157, 0x3e0293ee, v201
	v_exp_f32_e32 v173, v154
	v_fmamk_f32 v154, v158, 0x3e0293ee, v201
	v_exp_f32_e32 v174, v154
	v_fmamk_f32 v154, v159, 0x3e0293ee, v201
	v_exp_f32_e32 v175, v154
	v_fmamk_f32 v154, v160, 0x3e0293ee, v201
	v_exp_f32_e32 v176, v154
	v_fmamk_f32 v154, v161, 0x3e0293ee, v201
	v_exp_f32_e32 v177, v154
	v_fmamk_f32 v154, v162, 0x3e0293ee, v201
	v_exp_f32_e32 v178, v154
	v_fmamk_f32 v154, v163, 0x3e0293ee, v201
	v_exp_f32_e32 v179, v154
	v_fmamk_f32 v154, v164, 0x3e0293ee, v201
	v_exp_f32_e32 v180, v154
	v_fmamk_f32 v154, v165, 0x3e0293ee, v201
	v_exp_f32_e32 v181, v154
	v_fmamk_f32 v154, v166, 0x3e0293ee, v201
	v_exp_f32_e32 v182, v154
	v_fmamk_f32 v154, v167, 0x3e0293ee, v201
	v_exp_f32_e32 v183, v154
	v_fmamk_f32 v154, v168, 0x3e0293ee, v201
	v_exp_f32_e32 v184, v154
	v_fmac_f32_e32 v201, 0x3e0293ee, v169
	v_sub_f32_e32 v154, v233, v197
	v_exp_f32_e32 v154, v154
	s_nop 0
	v_cmp_neq_f32_e32 vcc, 1.0, v154
	s_cbranch_vccnz .LBB0_386
	s_branch .LBB0_387

.LBB0_399:
	v_max3_f32 v162, v138, v139, v140
	v_max3_f32 v163, v141, v142, v143
	v_max3_f32 v164, v144, v145, v146
	v_max3_f32 v162, v162, v163, v164
	v_max3_f32 v163, v147, v148, v149
	v_max3_f32 v164, v150, v151, v152
	v_max3_f32 v163, v163, v164, v153
	v_max_f32_e32 v162, v162, v163
	v_mov_b32_e32 v163, v162
	s_nop 1
	v_permlane16_swap_b32_e32 v163, v162
	v_max_f32_e32 v162, v162, v163
	v_mov_b32_e32 v163, v162
	s_nop 1
	v_permlane32_swap_b32_e32 v163, v162
	v_max_f32_e32 v162, v162, v163
	v_fmamk_f32 v162, v162, 0x3e0293ee, v248
	v_max_f32_e32 v178, v232, v162
	v_sub_f32_e32 v179, v248, v178
	v_fmamk_f32 v138, v138, 0x3e0293ee, v179
	v_exp_f32_e32 v162, v138
	v_fmamk_f32 v138, v139, 0x3e0293ee, v179
	v_exp_f32_e32 v163, v138
	v_fmamk_f32 v138, v140, 0x3e0293ee, v179
	v_exp_f32_e32 v164, v138
	v_fmamk_f32 v138, v141, 0x3e0293ee, v179
	v_exp_f32_e32 v165, v138
	v_fmamk_f32 v138, v142, 0x3e0293ee, v179
	v_exp_f32_e32 v170, v138
	v_fmamk_f32 v138, v143, 0x3e0293ee, v179
	v_exp_f32_e32 v171, v138
	v_fmamk_f32 v138, v144, 0x3e0293ee, v179
	v_exp_f32_e32 v172, v138
	v_fmamk_f32 v138, v145, 0x3e0293ee, v179
	v_exp_f32_e32 v173, v138
	v_fmamk_f32 v138, v146, 0x3e0293ee, v179
	v_exp_f32_e32 v166, v138
	v_fmamk_f32 v138, v147, 0x3e0293ee, v179
	v_exp_f32_e32 v167, v138
	v_fmamk_f32 v138, v148, 0x3e0293ee, v179
	v_exp_f32_e32 v168, v138
	v_fmamk_f32 v138, v149, 0x3e0293ee, v179
	v_exp_f32_e32 v169, v138
	v_fmamk_f32 v138, v150, 0x3e0293ee, v179
	v_exp_f32_e32 v174, v138
	v_fmamk_f32 v138, v151, 0x3e0293ee, v179
	v_exp_f32_e32 v175, v138
	v_fmamk_f32 v138, v152, 0x3e0293ee, v179
	v_exp_f32_e32 v176, v138
	v_fmac_f32_e32 v179, 0x3e0293ee, v153
	v_sub_f32_e32 v138, v232, v178
	v_exp_f32_e32 v138, v138
	s_nop 0
	v_cmp_neq_f32_e32 vcc, 1.0, v138
	s_cbranch_vccnz .LBB0_390
	s_branch .LBB0_391

.LBB0_441:
	s_setprio 0
	s_waitcnt vmcnt(0)
	v_readlane_b32 s60, v236, 36
	v_readlane_b32 s61, v236, 37
	s_mov_b64 s[92:93], s[6:7]
	v_readlane_b32 s94, v236, 39
	s_movk_i32 s61, 0x1000
	s_barrier
	v_readlane_b32 s95, v236, 40

.LBB0_459:
	s_cmp_eq_u32 s19, 1
	s_cbranch_scc0 .Lg0_noprio
	s_setprio 1

.LBB0_469:
	s_add_u32 s76, s82, 0xfff80080
	s_addc_u32 s77, s83, -1
	s_add_i32 s93, 0, 0x10000
	s_cmp_eq_u32 s74, 28
	s_cselect_b32 vcc_hi, s19, s77
	s_cselect_b32 vcc_lo, s69, s76
	v_add_u32_e32 v140, s93, v143
	v_add_u32_e32 v242, s93, v240
	s_cselect_b32 s77, s70, s73
	s_cselect_b32 s76, s71, s72
	s_add_i32 s75, 0, 0x14000
	ds_read_b128 v[146:149], v140
	ds_read_b128 v[150:153], v242
	ds_read_b128 v[154:157], v140 offset:2048
	ds_read_b128 v[158:161], v242 offset:2048
	v_add_u32_e32 v140, s75, v143
	v_add_u32_e32 v243, s75, v240
	ds_read_b128 v[162:165], v140
	ds_read_b128 v[166:169], v243
	ds_read_b128 v[170:173], v140 offset:2048
	ds_read_b128 v[174:177], v243 offset:2048
	v_lshl_add_u64 v[140:141], s[82:83], 0, v[138:139]
	s_add_i32 m0, s81, 0xc000
	ds_read_b128 v[178:181], v145
	ds_read_b128 v[182:185], v241
	ds_read_b128 v[190:193], v145 offset:2048
	ds_read_b128 v[194:197], v241 offset:2048
	ds_read_b128 v[198:201], v145 offset:4096
	ds_read_b128 v[216:219], v241 offset:4096
	ds_read_b128 v[220:223], v145 offset:6144
	ds_read_b128 v[224:227], v241 offset:6144
	global_load_lds_dwordx4 v[140:141], off
	v_lshl_add_u64 v[140:141], s[82:83], 0, v[136:137]
	s_add_i32 m0, s81, 0xe000
	s_nop 0
	global_load_lds_dwordx4 v[140:141], off
	s_waitcnt vmcnt(8)
	s_waitcnt lgkmcnt(0)
	s_barrier
	s_nop 0
	s_waitcnt lgkmcnt(0)
	v_mfma_f32_16x16x32_bf16 v[126:129], v[146:149], v[178:181], v[126:129]
	v_mfma_f32_16x16x32_bf16 v[122:125], v[154:157], v[178:181], v[122:125]
	v_mfma_f32_16x16x32_bf16 v[114:117], v[146:149], v[190:193], v[114:117]
	v_mfma_f32_16x16x32_bf16 v[106:109], v[154:157], v[190:193], v[106:109]
	v_mfma_f32_16x16x32_bf16 v[98:101], v[146:149], v[198:201], v[98:101]
	v_mfma_f32_16x16x32_bf16 v[90:93], v[154:157], v[198:201], v[90:93]
	v_mfma_f32_16x16x32_bf16 v[82:85], v[146:149], v[220:223], v[82:85]
	v_mfma_f32_16x16x32_bf16 v[74:77], v[154:157], v[220:223], v[74:77]
	v_mfma_f32_16x16x32_bf16 v[126:129], v[150:153], v[182:185], v[126:129]
	v_mfma_f32_16x16x32_bf16 v[122:125], v[158:161], v[182:185], v[122:125]
	v_mfma_f32_16x16x32_bf16 v[114:117], v[150:153], v[194:197], v[114:117]
	v_mfma_f32_16x16x32_bf16 v[106:109], v[158:161], v[194:197], v[106:109]
	v_mfma_f32_16x16x32_bf16 v[98:101], v[150:153], v[216:219], v[98:101]
	v_mfma_f32_16x16x32_bf16 v[90:93], v[158:161], v[216:219], v[90:93]
	v_mfma_f32_16x16x32_bf16 v[82:85], v[150:153], v[224:227], v[82:85]
	v_mfma_f32_16x16x32_bf16 v[74:77], v[158:161], v[224:227], v[74:77]
	s_nop 0
	s_nop 0
	v_mfma_f32_16x16x32_bf16 v[118:121], v[162:165], v[178:181], v[118:121]
	v_mfma_f32_16x16x32_bf16 v[110:113], v[170:173], v[178:181], v[110:113]
	v_mfma_f32_16x16x32_bf16 v[102:105], v[162:165], v[190:193], v[102:105]
	v_mfma_f32_16x16x32_bf16 v[94:97], v[170:173], v[190:193], v[94:97]
	v_mfma_f32_16x16x32_bf16 v[86:89], v[162:165], v[198:201], v[86:89]
	v_mfma_f32_16x16x32_bf16 v[78:81], v[170:173], v[198:201], v[78:81]
	v_mfma_f32_16x16x32_bf16 v[70:73], v[162:165], v[220:223], v[70:73]
	v_mfma_f32_16x16x32_bf16 v[66:69], v[170:173], v[220:223], v[66:69]
	v_mfma_f32_16x16x32_bf16 v[118:121], v[166:169], v[182:185], v[118:121]
	v_mfma_f32_16x16x32_bf16 v[110:113], v[174:177], v[182:185], v[110:113]
	v_mfma_f32_16x16x32_bf16 v[102:105], v[166:169], v[194:197], v[102:105]
	v_mfma_f32_16x16x32_bf16 v[94:97], v[174:177], v[194:197], v[94:97]
	v_mfma_f32_16x16x32_bf16 v[86:89], v[166:169], v[216:219], v[86:89]
	v_mfma_f32_16x16x32_bf16 v[78:81], v[174:177], v[216:219], v[78:81]
	v_mfma_f32_16x16x32_bf16 v[70:73], v[166:169], v[224:227], v[70:73]
	v_mfma_f32_16x16x32_bf16 v[66:69], v[174:177], v[224:227], v[66:69]
	s_nop 0
	s_barrier
	s_add_i32 s93, s93, s23
	v_lshl_add_u64 v[140:141], s[76:77], 0, v[0:1]
	s_mov_b32 m0, s93
	ds_read_b128 v[178:181], v145 offset:16384
	ds_read_b128 v[182:185], v241 offset:16384
	ds_read_b128 v[190:193], v145 offset:18432
	ds_read_b128 v[194:197], v241 offset:18432
	ds_read_b128 v[198:201], v145 offset:20480
	ds_read_b128 v[216:219], v241 offset:20480
	ds_read_b128 v[220:223], v145 offset:22528
	ds_read_b128 v[224:227], v241 offset:22528
	global_load_lds_dwordx4 v[140:141], off
	s_add_i32 m0, s93, 0x2000
	s_add_u32 s98, s76, 0x80000
	v_lshl_add_u64 v[202:203], s[76:77], 0, v[134:135]
	s_addc_u32 s99, s77, 0
	s_add_i32 s75, s75, s23
	global_load_lds_dwordx4 v[202:203], off
	v_lshl_add_u64 v[228:229], s[98:99], 0, v[0:1]
	s_mov_b32 m0, s75
	v_lshl_add_u64 v[230:231], vcc, 0, v[132:133]
	global_load_lds_dwordx4 v[228:229], off
	v_lshl_add_u64 v[228:229], s[98:99], 0, v[134:135]
	s_add_i32 m0, s75, 0x2000
	s_nop 0
	global_load_lds_dwordx4 v[228:229], off
	v_lshl_add_u64 v[228:229], vcc, 0, v[130:131]
	s_mov_b32 m0, s81
	s_nop 0
	global_load_lds_dwordx4 v[228:229], off
	s_mov_b32 m0, s60
	s_nop 0
	global_load_lds_dwordx4 v[230:231], off
	s_waitcnt vmcnt(8)
	s_waitcnt lgkmcnt(0)
	s_barrier
	s_nop 0
	s_waitcnt lgkmcnt(0)
	v_mfma_f32_16x16x32_bf16 v[62:65], v[146:149], v[178:181], v[62:65]
	v_mfma_f32_16x16x32_bf16 v[58:61], v[154:157], v[178:181], v[58:61]
	v_mfma_f32_16x16x32_bf16 v[46:49], v[146:149], v[190:193], v[46:49]
	v_mfma_f32_16x16x32_bf16 v[42:45], v[154:157], v[190:193], v[42:45]
	v_mfma_f32_16x16x32_bf16 v[30:33], v[146:149], v[198:201], v[30:33]
	v_mfma_f32_16x16x32_bf16 v[26:29], v[154:157], v[198:201], v[26:29]
	v_mfma_f32_16x16x32_bf16 v[14:17], v[146:149], v[220:223], v[14:17]
	v_mfma_f32_16x16x32_bf16 v[10:13], v[154:157], v[220:223], v[10:13]
	v_mfma_f32_16x16x32_bf16 v[62:65], v[150:153], v[182:185], v[62:65]
	v_mfma_f32_16x16x32_bf16 v[58:61], v[158:161], v[182:185], v[58:61]
	v_mfma_f32_16x16x32_bf16 v[46:49], v[150:153], v[194:197], v[46:49]
	v_mfma_f32_16x16x32_bf16 v[42:45], v[158:161], v[194:197], v[42:45]
	v_mfma_f32_16x16x32_bf16 v[30:33], v[150:153], v[216:219], v[30:33]
	v_mfma_f32_16x16x32_bf16 v[26:29], v[158:161], v[216:219], v[26:29]
	v_mfma_f32_16x16x32_bf16 v[14:17], v[150:153], v[224:227], v[14:17]
	v_mfma_f32_16x16x32_bf16 v[10:13], v[158:161], v[224:227], v[10:13]
	s_nop 0
	s_nop 0
	v_mfma_f32_16x16x32_bf16 v[54:57], v[162:165], v[178:181], v[54:57]
	v_mfma_f32_16x16x32_bf16 v[50:53], v[170:173], v[178:181], v[50:53]
	v_mfma_f32_16x16x32_bf16 v[38:41], v[162:165], v[190:193], v[38:41]
	v_mfma_f32_16x16x32_bf16 v[34:37], v[170:173], v[190:193], v[34:37]
	v_mfma_f32_16x16x32_bf16 v[22:25], v[162:165], v[198:201], v[22:25]
	v_mfma_f32_16x16x32_bf16 v[18:21], v[170:173], v[198:201], v[18:21]
	v_mfma_f32_16x16x32_bf16 v[6:9], v[162:165], v[220:223], v[6:9]
	v_mfma_f32_16x16x32_bf16 v[2:5], v[170:173], v[220:223], v[2:5]
	v_mfma_f32_16x16x32_bf16 v[54:57], v[166:169], v[182:185], v[54:57]
	v_mfma_f32_16x16x32_bf16 v[50:53], v[174:177], v[182:185], v[50:53]
	v_mfma_f32_16x16x32_bf16 v[38:41], v[166:169], v[194:197], v[38:41]
	v_mfma_f32_16x16x32_bf16 v[34:37], v[174:177], v[194:197], v[34:37]
	v_mfma_f32_16x16x32_bf16 v[22:25], v[166:169], v[216:219], v[22:25]
	v_mfma_f32_16x16x32_bf16 v[18:21], v[174:177], v[216:219], v[18:21]
	v_mfma_f32_16x16x32_bf16 v[6:9], v[166:169], v[224:227], v[6:9]
	v_mfma_f32_16x16x32_bf16 v[2:5], v[174:177], v[224:227], v[2:5]
	s_nop 0
	s_barrier
	s_add_i32 s75, 0, 0x18000
	s_add_i32 s93, 0, 0x1c000
	v_add_u32_e32 v158, s75, v143
	v_add_u32_e32 v242, s75, v240
	v_add_u32_e32 v174, s93, v143
	v_add_u32_e32 v243, s93, v240
	ds_read_b128 v[146:149], v158
	ds_read_b128 v[150:153], v242
	ds_read_b128 v[154:157], v158 offset:2048
	ds_read_b128 v[158:161], v242 offset:2048
	ds_read_b128 v[162:165], v174
	ds_read_b128 v[166:169], v243
	ds_read_b128 v[170:173], v174 offset:2048
	ds_read_b128 v[174:177], v243 offset:2048
	s_add_u32 s98, vcc_lo, 0x80000
	s_addc_u32 s99, vcc_hi, 0
	s_mov_b32 m0, s61
	v_lshl_add_u64 v[232:233], s[98:99], 0, v[130:131]
	ds_read_b128 v[178:181], v145 offset:32768
	ds_read_b128 v[182:185], v241 offset:32768
	ds_read_b128 v[190:193], v145 offset:34816
	ds_read_b128 v[194:197], v241 offset:34816
	ds_read_b128 v[198:201], v145 offset:36864
	ds_read_b128 v[216:219], v241 offset:36864
	ds_read_b128 v[220:223], v145 offset:38912
	ds_read_b128 v[224:227], v241 offset:38912
	global_load_lds_dwordx4 v[232:233], off
	v_lshl_add_u64 v[232:233], s[98:99], 0, v[132:133]
	s_mov_b32 m0, s64
	s_nop 0
	global_load_lds_dwordx4 v[232:233], off
	s_waitcnt vmcnt(8)
	s_waitcnt lgkmcnt(0)
	s_barrier
	s_nop 0
	s_waitcnt lgkmcnt(0)
	v_mfma_f32_16x16x32_bf16 v[126:129], v[146:149], v[178:181], v[126:129]
	v_mfma_f32_16x16x32_bf16 v[122:125], v[154:157], v[178:181], v[122:125]
	v_mfma_f32_16x16x32_bf16 v[114:117], v[146:149], v[190:193], v[114:117]
	v_mfma_f32_16x16x32_bf16 v[106:109], v[154:157], v[190:193], v[106:109]
	v_mfma_f32_16x16x32_bf16 v[98:101], v[146:149], v[198:201], v[98:101]
	v_mfma_f32_16x16x32_bf16 v[90:93], v[154:157], v[198:201], v[90:93]
	v_mfma_f32_16x16x32_bf16 v[82:85], v[146:149], v[220:223], v[82:85]
	v_mfma_f32_16x16x32_bf16 v[74:77], v[154:157], v[220:223], v[74:77]
	v_mfma_f32_16x16x32_bf16 v[126:129], v[150:153], v[182:185], v[126:129]
	v_mfma_f32_16x16x32_bf16 v[122:125], v[158:161], v[182:185], v[122:125]
	v_mfma_f32_16x16x32_bf16 v[114:117], v[150:153], v[194:197], v[114:117]
	v_mfma_f32_16x16x32_bf16 v[106:109], v[158:161], v[194:197], v[106:109]
	v_mfma_f32_16x16x32_bf16 v[98:101], v[150:153], v[216:219], v[98:101]
	v_mfma_f32_16x16x32_bf16 v[90:93], v[158:161], v[216:219], v[90:93]
	v_mfma_f32_16x16x32_bf16 v[82:85], v[150:153], v[224:227], v[82:85]
	v_mfma_f32_16x16x32_bf16 v[74:77], v[158:161], v[224:227], v[74:77]
	s_nop 0
	s_nop 0
	v_mfma_f32_16x16x32_bf16 v[118:121], v[162:165], v[178:181], v[118:121]
	v_mfma_f32_16x16x32_bf16 v[110:113], v[170:173], v[178:181], v[110:113]
	v_mfma_f32_16x16x32_bf16 v[102:105], v[162:165], v[190:193], v[102:105]
	v_mfma_f32_16x16x32_bf16 v[94:97], v[170:173], v[190:193], v[94:97]
	v_mfma_f32_16x16x32_bf16 v[86:89], v[162:165], v[198:201], v[86:89]
	v_mfma_f32_16x16x32_bf16 v[78:81], v[170:173], v[198:201], v[78:81]
	v_mfma_f32_16x16x32_bf16 v[70:73], v[162:165], v[220:223], v[70:73]
	v_mfma_f32_16x16x32_bf16 v[66:69], v[170:173], v[220:223], v[66:69]
	v_mfma_f32_16x16x32_bf16 v[118:121], v[166:169], v[182:185], v[118:121]
	v_mfma_f32_16x16x32_bf16 v[110:113], v[174:177], v[182:185], v[110:113]
	v_mfma_f32_16x16x32_bf16 v[102:105], v[166:169], v[194:197], v[102:105]
	v_mfma_f32_16x16x32_bf16 v[94:97], v[174:177], v[194:197], v[94:97]
	v_mfma_f32_16x16x32_bf16 v[86:89], v[166:169], v[216:219], v[86:89]
	v_mfma_f32_16x16x32_bf16 v[78:81], v[174:177], v[216:219], v[78:81]
	v_mfma_f32_16x16x32_bf16 v[70:73], v[166:169], v[224:227], v[70:73]
	v_mfma_f32_16x16x32_bf16 v[66:69], v[174:177], v[224:227], v[66:69]
	s_nop 0
	s_barrier
	s_add_i32 s75, s75, s23
	v_lshl_add_u64 v[140:141], v[140:141], 0, s[20:21]
	s_mov_b32 m0, s75
	ds_read_b128 v[178:181], v145 offset:49152
	ds_read_b128 v[182:185], v241 offset:49152
	ds_read_b128 v[190:193], v145 offset:51200
	ds_read_b128 v[194:197], v241 offset:51200
	ds_read_b128 v[198:201], v145 offset:53248
	ds_read_b128 v[216:219], v241 offset:53248
	ds_read_b128 v[220:223], v145 offset:55296
	ds_read_b128 v[224:227], v241 offset:55296
	global_load_lds_dwordx4 v[140:141], off
	s_add_i32 m0, s75, 0x2000
	s_add_u32 s76, s76, 0x80080
	v_lshl_add_u64 v[140:141], v[202:203], 0, s[20:21]
	s_addc_u32 s77, s77, 0
	s_add_i32 s75, s93, s23
	global_load_lds_dwordx4 v[140:141], off
	v_lshl_add_u64 v[140:141], s[76:77], 0, v[0:1]
	s_mov_b32 m0, s75
	s_nop 0
	global_load_lds_dwordx4 v[140:141], off
	v_lshl_add_u64 v[140:141], s[76:77], 0, v[134:135]
	s_add_i32 m0, s75, 0x2000
	s_nop 0
	global_load_lds_dwordx4 v[140:141], off
	v_lshl_add_u64 v[140:141], v[228:229], 0, s[20:21]
	s_mov_b32 m0, s65
	s_nop 0
	global_load_lds_dwordx4 v[140:141], off
	v_lshl_add_u64 v[140:141], v[230:231], 0, s[20:21]
	s_mov_b32 m0, s66
	s_nop 0
	global_load_lds_dwordx4 v[140:141], off
	s_waitcnt vmcnt(8)
	s_waitcnt lgkmcnt(0)
	s_barrier
	s_nop 0
	s_waitcnt lgkmcnt(0)
	v_mfma_f32_16x16x32_bf16 v[62:65], v[146:149], v[178:181], v[62:65]
	v_mfma_f32_16x16x32_bf16 v[58:61], v[154:157], v[178:181], v[58:61]
	v_mfma_f32_16x16x32_bf16 v[46:49], v[146:149], v[190:193], v[46:49]
	v_mfma_f32_16x16x32_bf16 v[42:45], v[154:157], v[190:193], v[42:45]
	v_mfma_f32_16x16x32_bf16 v[30:33], v[146:149], v[198:201], v[30:33]
	v_mfma_f32_16x16x32_bf16 v[26:29], v[154:157], v[198:201], v[26:29]
	v_mfma_f32_16x16x32_bf16 v[14:17], v[146:149], v[220:223], v[14:17]
	v_mfma_f32_16x16x32_bf16 v[10:13], v[154:157], v[220:223], v[10:13]
	v_mfma_f32_16x16x32_bf16 v[62:65], v[150:153], v[182:185], v[62:65]
	v_mfma_f32_16x16x32_bf16 v[58:61], v[158:161], v[182:185], v[58:61]
	v_mfma_f32_16x16x32_bf16 v[46:49], v[150:153], v[194:197], v[46:49]
	v_mfma_f32_16x16x32_bf16 v[42:45], v[158:161], v[194:197], v[42:45]
	v_mfma_f32_16x16x32_bf16 v[30:33], v[150:153], v[216:219], v[30:33]
	v_mfma_f32_16x16x32_bf16 v[26:29], v[158:161], v[216:219], v[26:29]
	v_mfma_f32_16x16x32_bf16 v[14:17], v[150:153], v[224:227], v[14:17]
	v_mfma_f32_16x16x32_bf16 v[10:13], v[158:161], v[224:227], v[10:13]
	s_nop 0
	s_nop 0
	v_mfma_f32_16x16x32_bf16 v[54:57], v[162:165], v[178:181], v[54:57]
	v_mfma_f32_16x16x32_bf16 v[50:53], v[170:173], v[178:181], v[50:53]
	v_mfma_f32_16x16x32_bf16 v[38:41], v[162:165], v[190:193], v[38:41]
	v_mfma_f32_16x16x32_bf16 v[34:37], v[170:173], v[190:193], v[34:37]
	v_mfma_f32_16x16x32_bf16 v[22:25], v[162:165], v[198:201], v[22:25]
	v_mfma_f32_16x16x32_bf16 v[18:21], v[170:173], v[198:201], v[18:21]
	v_mfma_f32_16x16x32_bf16 v[6:9], v[162:165], v[220:223], v[6:9]
	v_mfma_f32_16x16x32_bf16 v[2:5], v[170:173], v[220:223], v[2:5]
	v_mfma_f32_16x16x32_bf16 v[54:57], v[166:169], v[182:185], v[54:57]
	v_mfma_f32_16x16x32_bf16 v[50:53], v[174:177], v[182:185], v[50:53]
	v_mfma_f32_16x16x32_bf16 v[38:41], v[166:169], v[194:197], v[38:41]
	v_mfma_f32_16x16x32_bf16 v[34:37], v[174:177], v[194:197], v[34:37]
	v_mfma_f32_16x16x32_bf16 v[22:25], v[166:169], v[216:219], v[22:25]
	v_mfma_f32_16x16x32_bf16 v[18:21], v[174:177], v[216:219], v[18:21]
	v_mfma_f32_16x16x32_bf16 v[6:9], v[166:169], v[224:227], v[6:9]
	v_mfma_f32_16x16x32_bf16 v[2:5], v[174:177], v[224:227], v[2:5]
	s_nop 0
	s_barrier
	s_add_i32 s74, s74, 2
	s_add_u32 s72, s72, 0x100
	s_addc_u32 s73, s73, 0
	s_add_u32 s82, s82, 0x100
	s_addc_u32 s83, s83, 0
	s_cmp_gt_u32 s74, 29
	s_cbranch_scc0 .LBB0_469
	s_and_b64 vcc, exec, s[94:95]
	s_cbranch_vccz .LBB0_472
	s_barrier
